# sc1+nt stores in both norm phases on top of v111
# baseline (speedup 1.0000x reference)
;     __device__ __forceinline__ const float* in(int i) const { return (const float*)(const __attribute__((address_space(1))) float*)ld(i); }
;     __device__ __forceinline__ unsigned char* ws() const { return (unsigned char*)(__attribute__((address_space(1))) unsigned char*)ld(23); }
; __device__ __forceinline__ unsigned pk2(float lo, float hi) { return cvtpk(lo, hi); }
; #define LDS_WAIT() asm volatile("s_waitcnt lgkmcnt(0)" ::: "memory")
; template <bool UPMAP>
; __device__ __forceinline__ void transpose_item(const float* W, int K, int N, bf16* WT, float* scr, int item, int lane) {
;     const int nblk = N / 32, kb = item / nblk, nb = item % nblk, k0 = 64 * kb, n0 = 32 * nb;
;     { f32x4 v[8];
; #pragma unroll
;       for (int i = 0; i < 8; ++i) v[i] = *(const f32x4*)(W + (size_t)(k0 + 8 * i + (lane >> 3)) * N + n0 + 4 * (lane & 7));
; #pragma unroll
;       for (int i = 0; i < 8; ++i) { float* d = scr + (8 * i + (lane >> 3)) * 33 + 4 * (lane & 7); d[0] = v[i][0]; d[1] = v[i][1]; d[2] = v[i][2]; d[3] = v[i][3]; } }
;     LDS_WAIT();
;     const int c = lane & 7;
; #pragma unroll
;     for (int j = 0; j < 4; ++j) { const int n = (lane >> 3) + 8 * j; const float* s = scr + (8 * c) * 33 + n;
;         v4u o; o.x = pk2(s[0 * 33], s[1 * 33]); o.y = pk2(s[2 * 33], s[3 * 33]); o.z = pk2(s[4 * 33], s[5 * 33]); o.w = pk2(s[6 * 33], s[7 * 33]);
;         const int nsrc = n0 + n; int nrow = nsrc;
;         if (UPMAP) { const int bj = nsrc / 2816, chn = nsrc - bj * 2816; nrow = (chn >> 7) * 256 + bj * 128 + (chn & 127); }
;         *(v4u*)(WT + (size_t)nrow * K + k0 + 8 * c) = o; }
;     LDS_WAIT();
; template <int PART>
; __device__ __forceinline__ void prologue(const KPD& kp, unsigned char* lds, int tid, int lane, int wave) {
;     ...
;         transpose_item<false>(kp.in(I_WDOWN) + (size_t)l * DFF * D, DFF, D, (bf16*)(ws + WS_WDN) + (size_t)l * D * DFF, scr, r, lane);
.LBB0_90:
	s_mul_hi_i32 s2, s17, 0x5ac5242b
	s_lshr_b32 s3, s2, 31
	s_ashr_i32 s2, s2, 11
	s_add_i32 s2, s2, s3
	s_mul_i32 s3, s2, 0xffffe970
	s_add_i32 s18, s17, s3
	s_cmpk_gt_i32 s18, 0x40f
	s_mov_b64 s[4:5], -1
	s_cbranch_scc0 .LBB0_100
	s_cmpk_gt_u32 s18, 0x60f
	s_cbranch_scc0 .LBB0_97
	s_cmpk_gt_u32 s18, 0x110f
	s_cbranch_scc0 .LBB0_94
	v_mov_b32_e32 v26, 0x264a8
	ds_read_b64 v[26:27], v26
	s_mul_i32 s4, s2, 0xb00000
	s_mul_hi_i32 s3, s2, 0xb00000
	s_mul_hi_i32 s5, s2, 0x580000
	v_lshlrev_b32_e32 v34, 2, v2
	s_waitcnt lgkmcnt(0)
	v_readfirstlane_b32 s20, v26
	v_readfirstlane_b32 s19, v27
	s_add_u32 s4, s20, s4
	s_addc_u32 s19, s19, s3
	s_mul_i32 s3, s2, 0x580000
	s_add_u32 s20, s6, s3
	s_addc_u32 s21, s7, s5
	s_add_i32 s3, s18, 0xeef0
	s_bfe_u32 s22, s3, 0xb0005
	s_lshl_b32 s3, s3, 5
	s_and_b32 s3, s3, 0x3e0
	s_lshl_b32 s5, s3, 2
	s_add_u32 s4, s4, s5
	s_addc_u32 s5, s19, 0
	v_lshl_add_u64 v[26:27], s[4:5], 0, v[34:35]
	v_lshl_or_b32 v34, s22, 18, v10
	v_lshl_add_u64 v[36:37], v[26:27], 0, v[34:35]
	s_mov_b32 s4, 0x8000
	v_add_co_u32_e32 v30, vcc, s4, v36
	s_mov_b32 s4, 0x10000
	s_nop 0
	v_addc_co_u32_e32 v31, vcc, 0, v37, vcc
	v_add_co_u32_e32 v42, vcc, s4, v36
	s_mov_b32 s4, 0x18000
	s_nop 0
	v_addc_co_u32_e32 v43, vcc, 0, v37, vcc
	v_add_co_u32_e32 v46, vcc, s4, v36
	s_mov_b32 s4, 0x20000
	s_nop 0
	v_addc_co_u32_e32 v47, vcc, 0, v37, vcc
	v_add_co_u32_e32 v50, vcc, s4, v36
	s_mov_b32 s4, 0x28000
	s_nop 0
	v_addc_co_u32_e32 v51, vcc, 0, v37, vcc
	v_add_co_u32_e32 v54, vcc, s4, v36
	global_load_dwordx4 v[26:29], v[36:37], off
	s_nop 0
	global_load_dwordx4 v[30:33], v[30:31], off
	v_addc_co_u32_e32 v55, vcc, 0, v37, vcc
	global_load_dwordx4 v[42:45], v[42:43], off
	s_nop 0
	global_load_dwordx4 v[46:49], v[46:47], off
	s_nop 0
	global_load_dwordx4 v[50:53], v[50:51], off
	s_nop 0
	global_load_dwordx4 v[54:57], v[54:55], off
	s_mov_b32 s4, 0x30000
	v_add_co_u32_e32 v58, vcc, s4, v36
	s_mov_b32 s4, 0x38000
	s_nop 0
	v_addc_co_u32_e32 v59, vcc, 0, v37, vcc
	global_load_dwordx4 v[58:61], v[58:59], off
	v_add_co_u32_e32 v36, vcc, s4, v36
	s_lshl_b32 s4, s22, 7
	s_nop 0
	v_addc_co_u32_e32 v37, vcc, 0, v37, vcc
	global_load_dwordx4 v[62:65], v[36:37], off
	v_or_b32_e32 v34, s3, v5
	s_add_u32 s4, s20, s4
	v_or_b32_e32 v36, s3, v6
	v_mul_u32_u24_e32 v38, 0xb00, v34
	s_addc_u32 s5, s21, 0
	v_lshlrev_b32_e32 v34, 1, v4
	v_mul_u32_u24_e32 v39, 0xb00, v36
	v_lshl_add_u64 v[36:37], s[4:5], 0, v[34:35]
	v_lshlrev_b32_e32 v34, 1, v38
	v_lshl_add_u64 v[66:67], v[36:37], 0, v[34:35]
	v_lshlrev_b32_e32 v34, 1, v39
	v_lshl_add_u64 v[68:69], v[36:37], 0, v[34:35]
	s_mov_b64 s[4:5], 0
	s_waitcnt vmcnt(7)
	ds_write2_b32 v11, v26, v27 offset1:1
	ds_write2_b32 v11, v28, v29 offset0:2 offset1:3
	s_waitcnt vmcnt(6)
	ds_write2_b32 v12, v30, v31 offset1:1
	ds_write2_b32 v13, v32, v33 offset1:1
	s_waitcnt vmcnt(5)
	ds_write2_b32 v14, v42, v43 offset1:1
	ds_write2_b32 v15, v44, v45 offset1:1
	s_waitcnt vmcnt(4)
	ds_write2_b32 v16, v46, v47 offset1:1
	ds_write2_b32 v17, v48, v49 offset1:1
	s_waitcnt vmcnt(3)
	ds_write2_b32 v18, v50, v51 offset1:1
	ds_write2_b32 v19, v52, v53 offset1:1
	s_waitcnt vmcnt(2)
	ds_write2_b32 v20, v54, v55 offset1:1
	ds_write2_b32 v21, v56, v57 offset1:1
	s_waitcnt vmcnt(1)
	ds_write2_b32 v22, v58, v59 offset1:1
	ds_write2_b32 v23, v60, v61 offset1:1
	s_waitcnt vmcnt(0)
	ds_write2_b32 v24, v62, v63 offset1:1
	ds_write2_b32 v25, v64, v65 offset1:1
	s_waitcnt lgkmcnt(0)
	ds_read2_b32 v[30:31], v9 offset0:33 offset1:41
	ds_read2_b32 v[32:33], v9 offset1:8
	ds_read2_b32 v[42:43], v9 offset0:66 offset1:74
	ds_read2_b32 v[44:45], v9 offset0:99 offset1:107
	ds_read2_b32 v[46:47], v9 offset0:132 offset1:140
	ds_read2_b32 v[48:49], v9 offset0:165 offset1:173
	ds_read2_b32 v[50:51], v9 offset0:198 offset1:206
	ds_read2_b32 v[52:53], v9 offset0:231 offset1:239
	ds_read2_b32 v[54:55], v9 offset0:16 offset1:24
	ds_read2_b32 v[56:57], v9 offset0:49 offset1:57
	s_waitcnt lgkmcnt(8)
	v_cvt_pk_bf16_f32 v26, v32, v30
	s_waitcnt lgkmcnt(6)
	v_cvt_pk_bf16_f32 v27, v42, v44
	s_waitcnt lgkmcnt(4)
	v_cvt_pk_bf16_f32 v28, v46, v48
	s_waitcnt lgkmcnt(2)
	v_cvt_pk_bf16_f32 v29, v50, v52
	global_store_dwordx4 v[66:67], v[26:29], off sc1 nt
	v_cvt_pk_bf16_f32 v30, v33, v31
	v_cvt_pk_bf16_f32 v31, v43, v45
	v_cvt_pk_bf16_f32 v32, v47, v49
	v_cvt_pk_bf16_f32 v33, v51, v53
	ds_read2_b32 v[42:43], v9 offset0:82 offset1:90
	ds_read2_b32 v[44:45], v9 offset0:115 offset1:123
	ds_read2_b32 v[46:47], v9 offset0:148 offset1:156
	ds_read2_b32 v[48:49], v9 offset0:181 offset1:189
	ds_read2_b32 v[50:51], v9 offset0:214 offset1:222
	ds_read2_b32 v[52:53], v9 offset0:247 offset1:255
	global_store_dwordx4 v[68:69], v[30:33], off sc1 nt
	s_waitcnt lgkmcnt(6)
	v_cvt_pk_bf16_f32 v26, v54, v56
	s_waitcnt lgkmcnt(4)
	v_cvt_pk_bf16_f32 v27, v42, v44
	s_waitcnt lgkmcnt(2)
	v_cvt_pk_bf16_f32 v28, v46, v48
	s_waitcnt lgkmcnt(0)
	v_cvt_pk_bf16_f32 v29, v50, v52
	v_or_b32_e32 v30, s3, v7
	v_mul_u32_u24_e32 v30, 0xb00, v30
	v_lshlrev_b32_e32 v34, 1, v30
	v_lshl_add_u64 v[30:31], v[36:37], 0, v[34:35]
	global_store_dwordx4 v[30:31], v[26:29], off sc1 nt
	v_or_b32_e32 v30, s3, v8
	v_mul_u32_u24_e32 v30, 0xb00, v30
	v_lshlrev_b32_e32 v34, 1, v30
	v_lshl_add_u64 v[30:31], v[36:37], 0, v[34:35]
	v_cvt_pk_bf16_f32 v26, v55, v57
	v_cvt_pk_bf16_f32 v27, v43, v45
	v_cvt_pk_bf16_f32 v28, v47, v49
	v_cvt_pk_bf16_f32 v29, v51, v53
	global_store_dwordx4 v[30:31], v[26:29], off sc1 nt
	s_waitcnt lgkmcnt(0)
;     __device__ __forceinline__ const float* in(int i) const { return (const float*)(const __attribute__((address_space(1))) float*)ld(i); }
;     __device__ __forceinline__ unsigned char* ws() const { return (unsigned char*)(__attribute__((address_space(1))) unsigned char*)ld(23); }
; __device__ __forceinline__ unsigned pk2(float lo, float hi) { return cvtpk(lo, hi); }
; #define LDS_WAIT() asm volatile("s_waitcnt lgkmcnt(0)" ::: "memory")
; template <bool UPMAP>
; __device__ __forceinline__ void transpose_item(const float* W, int K, int N, bf16* WT, float* scr, int item, int lane) {
;     const int nblk = N / 32, kb = item / nblk, nb = item % nblk, k0 = 64 * kb, n0 = 32 * nb;
;     { f32x4 v[8];
; #pragma unroll
;       for (int i = 0; i < 8; ++i) v[i] = *(const f32x4*)(W + (size_t)(k0 + 8 * i + (lane >> 3)) * N + n0 + 4 * (lane & 7));
; #pragma unroll
;       for (int i = 0; i < 8; ++i) { float* d = scr + (8 * i + (lane >> 3)) * 33 + 4 * (lane & 7); d[0] = v[i][0]; d[1] = v[i][1]; d[2] = v[i][2]; d[3] = v[i][3]; } }
;     LDS_WAIT();
;     const int c = lane & 7;
; #pragma unroll
;     for (int j = 0; j < 4; ++j) { const int n = (lane >> 3) + 8 * j; const float* s = scr + (8 * c) * 33 + n;
;         v4u o; o.x = pk2(s[0 * 33], s[1 * 33]); o.y = pk2(s[2 * 33], s[3 * 33]); o.z = pk2(s[4 * 33], s[5 * 33]); o.w = pk2(s[6 * 33], s[7 * 33]);
;         const int nsrc = n0 + n; int nrow = nsrc;
;         if (UPMAP) { const int bj = nsrc / 2816, chn = nsrc - bj * 2816; nrow = (chn >> 7) * 256 + bj * 128 + (chn & 127); }
;         *(v4u*)(WT + (size_t)nrow * K + k0 + 8 * c) = o; }
;     LDS_WAIT();
; template <int PART>
; __device__ __forceinline__ void prologue(const KPD& kp, unsigned char* lds, int tid, int lane, int wave) {
;     ...
;         if (r < I_UP) { transpose_item<true>(kp.in(I_WUP) + (size_t)l * D * DFF2, D, DFF2, (bf16*)(ws + WS_WUP) + (size_t)l * DFF2 * D, scr, r, lane); continue; } r -= I_UP;
.LBB0_94:
	s_andn2_b64 vcc, exec, s[4:5]
	s_cbranch_vccnz .LBB0_96
	v_mov_b32_e32 v26, 0x26490
	ds_read_b64 v[26:27], v26
	s_mul_i32 s4, s2, 0x1600000
	s_mul_hi_i32 s3, s2, 0x1600000
	s_mul_hi_i32 s5, s2, 0xb00000
	v_lshlrev_b32_e32 v34, 2, v2
	s_waitcnt lgkmcnt(0)
	v_readfirstlane_b32 s20, v26
	v_readfirstlane_b32 s19, v27
	s_add_u32 s4, s20, s4
	s_addc_u32 s3, s19, s3
	s_mul_i32 s19, s2, 0xb00000
	s_add_u32 s19, s9, s19
	s_addc_u32 s20, s10, s5
	s_add_i32 s5, s18, 0xf9f0
	s_and_b32 s21, s5, 0xffff
	s_mul_i32 s21, s21, 0xba2f
	s_lshr_b32 s21, s21, 23
	s_mul_i32 s22, s21, 0xb0
	s_sub_i32 s22, s5, s22
	s_lshl_b32 s23, s22, 5
	s_and_b32 s24, s23, 0xffe0
	s_lshl_b32 s5, s24, 2
	v_lshl_or_b32 v28, s21, 6, v5
	s_add_u32 s4, s4, s5
	s_addc_u32 s5, s3, 0
	v_mul_u32_u24_e32 v28, 0x1600, v28
	v_lshl_add_u64 v[26:27], s[4:5], 0, v[34:35]
	v_lshlrev_b32_e32 v34, 2, v28
	v_lshl_add_u64 v[36:37], v[26:27], 0, v[34:35]
	s_mov_b32 s3, 0x2c000
	v_add_co_u32_e32 v30, vcc, s3, v36
	s_mov_b32 s3, 0x58000
	s_nop 0
	v_addc_co_u32_e32 v31, vcc, 0, v37, vcc
	v_add_co_u32_e32 v42, vcc, s3, v36
	s_mov_b32 s3, 0x84000
	s_nop 0
	v_addc_co_u32_e32 v43, vcc, 0, v37, vcc
	v_add_co_u32_e32 v46, vcc, s3, v36
	s_mov_b32 s3, 0xb0000
	s_nop 0
	v_addc_co_u32_e32 v47, vcc, 0, v37, vcc
	v_add_co_u32_e32 v50, vcc, s3, v36
	s_mov_b32 s3, 0xdc000
	s_nop 0
	v_addc_co_u32_e32 v51, vcc, 0, v37, vcc
	v_add_co_u32_e32 v54, vcc, s3, v36
	global_load_dwordx4 v[26:29], v[36:37], off
	s_nop 0
	global_load_dwordx4 v[30:33], v[30:31], off
	v_addc_co_u32_e32 v55, vcc, 0, v37, vcc
	global_load_dwordx4 v[42:45], v[42:43], off
	s_nop 0
	global_load_dwordx4 v[46:49], v[46:47], off
	s_nop 0
	global_load_dwordx4 v[50:53], v[50:51], off
	s_nop 0
	global_load_dwordx4 v[54:57], v[54:55], off
	s_mov_b32 s3, 0x108000
	v_add_co_u32_e32 v58, vcc, s3, v36
	s_mov_b32 s3, 0x134000
	s_nop 0
	v_addc_co_u32_e32 v59, vcc, 0, v37, vcc
	global_load_dwordx4 v[58:61], v[58:59], off
	v_add_co_u32_e32 v36, vcc, s3, v36
	s_and_b32 s3, s22, 0xffff
	s_nop 0
	v_addc_co_u32_e32 v37, vcc, 0, v37, vcc
	global_load_dwordx4 v[62:65], v[36:37], off
	s_cmpk_gt_u32 s3, 0x57
	s_cselect_b32 s3, 0xfffff500, 0
	s_cselect_b32 s22, 0x80, 0
	s_lshl_b32 s4, s21, 7
	s_add_u32 s4, s19, s4
	s_addc_u32 s5, s20, 0
	s_add_i32 s3, s3, s24
	v_lshlrev_b32_e32 v34, 1, v4
	s_and_b32 s19, s23, 0x60
	s_lshl_b32 s3, s3, 1
	v_lshl_add_u64 v[36:37], s[4:5], 0, v[34:35]
	s_or_b32 s4, s19, s22
	s_and_b32 s3, s3, 0xffffff00
	s_or_b32 s3, s4, s3
	v_or_b32_e32 v66, s3, v5
	v_ashrrev_i32_e32 v67, 31, v66
	s_waitcnt vmcnt(7)
	ds_write2_b32 v11, v26, v27 offset1:1
	ds_write2_b32 v11, v28, v29 offset0:2 offset1:3
	s_waitcnt vmcnt(6)
	ds_write2_b32 v12, v30, v31 offset1:1
	ds_write2_b32 v13, v32, v33 offset1:1
	s_waitcnt vmcnt(5)
	ds_write2_b32 v14, v42, v43 offset1:1
	ds_write2_b32 v15, v44, v45 offset1:1
	s_waitcnt vmcnt(4)
	ds_write2_b32 v16, v46, v47 offset1:1
	ds_write2_b32 v17, v48, v49 offset1:1
	s_waitcnt vmcnt(3)
	ds_write2_b32 v18, v50, v51 offset1:1
	ds_write2_b32 v19, v52, v53 offset1:1
	s_waitcnt vmcnt(2)
	ds_write2_b32 v20, v54, v55 offset1:1
	ds_write2_b32 v21, v56, v57 offset1:1
	s_waitcnt vmcnt(1)
	ds_write2_b32 v22, v58, v59 offset1:1
	ds_write2_b32 v23, v60, v61 offset1:1
	s_waitcnt vmcnt(0)
	ds_write2_b32 v24, v62, v63 offset1:1
	ds_write2_b32 v25, v64, v65 offset1:1
	s_waitcnt lgkmcnt(0)
	ds_read2_b32 v[30:31], v9 offset0:33 offset1:41
	ds_read2_b32 v[32:33], v9 offset1:8
	ds_read2_b32 v[42:43], v9 offset0:66 offset1:74
	ds_read2_b32 v[44:45], v9 offset0:99 offset1:107
	ds_read2_b32 v[46:47], v9 offset0:132 offset1:140
	ds_read2_b32 v[48:49], v9 offset0:165 offset1:173
	ds_read2_b32 v[50:51], v9 offset0:198 offset1:206
	ds_read2_b32 v[52:53], v9 offset0:231 offset1:239
	v_lshlrev_b64 v[54:55], 11, v[66:67]
	s_waitcnt lgkmcnt(6)
	v_cvt_pk_bf16_f32 v26, v32, v30
	v_lshl_add_u64 v[54:55], v[36:37], 0, v[54:55]
	v_or_b32_e32 v30, s3, v6
	s_waitcnt lgkmcnt(4)
	v_cvt_pk_bf16_f32 v27, v42, v44
	s_waitcnt lgkmcnt(2)
	v_cvt_pk_bf16_f32 v28, v46, v48
	s_waitcnt lgkmcnt(0)
	v_cvt_pk_bf16_f32 v29, v50, v52
	global_store_dwordx4 v[54:55], v[26:29], off sc1 nt
	s_nop 1
	v_cvt_pk_bf16_f32 v26, v33, v31
	v_ashrrev_i32_e32 v31, 31, v30
	v_lshlrev_b64 v[30:31], 11, v[30:31]
	v_cvt_pk_bf16_f32 v27, v43, v45
	v_cvt_pk_bf16_f32 v28, v47, v49
	v_cvt_pk_bf16_f32 v29, v51, v53
	v_lshl_add_u64 v[30:31], v[36:37], 0, v[30:31]
	ds_read2_b32 v[32:33], v9 offset0:16 offset1:24
	ds_read2_b32 v[42:43], v9 offset0:49 offset1:57
	ds_read2_b32 v[44:45], v9 offset0:82 offset1:90
	ds_read2_b32 v[46:47], v9 offset0:115 offset1:123
	ds_read2_b32 v[48:49], v9 offset0:148 offset1:156
	ds_read2_b32 v[50:51], v9 offset0:181 offset1:189
	ds_read2_b32 v[52:53], v9 offset0:214 offset1:222
	ds_read2_b32 v[54:55], v9 offset0:247 offset1:255
	global_store_dwordx4 v[30:31], v[26:29], off sc1 nt
	v_or_b32_e32 v30, s3, v7
	v_ashrrev_i32_e32 v31, 31, v30
	v_lshlrev_b64 v[30:31], 11, v[30:31]
	v_lshl_add_u64 v[30:31], v[36:37], 0, v[30:31]
	s_waitcnt lgkmcnt(6)
	v_cvt_pk_bf16_f32 v26, v32, v42
	s_waitcnt lgkmcnt(4)
	v_cvt_pk_bf16_f32 v27, v44, v46
	s_waitcnt lgkmcnt(2)
	v_cvt_pk_bf16_f32 v28, v48, v50
	s_waitcnt lgkmcnt(0)
	v_cvt_pk_bf16_f32 v29, v52, v54
	global_store_dwordx4 v[30:31], v[26:29], off sc1 nt
	v_or_b32_e32 v30, s3, v8
	v_ashrrev_i32_e32 v31, 31, v30
	v_lshlrev_b64 v[30:31], 11, v[30:31]
	v_lshl_add_u64 v[30:31], v[36:37], 0, v[30:31]
	v_cvt_pk_bf16_f32 v26, v33, v43
	v_cvt_pk_bf16_f32 v27, v45, v47
	v_cvt_pk_bf16_f32 v28, v49, v51
	v_cvt_pk_bf16_f32 v29, v53, v55
	global_store_dwordx4 v[30:31], v[26:29], off sc1 nt
	s_waitcnt lgkmcnt(0)

;     __device__ __forceinline__ const float* in(int i) const { return (const float*)(const __attribute__((address_space(1))) float*)ld(i); }
;     __device__ __forceinline__ unsigned char* ws() const { return (unsigned char*)(__attribute__((address_space(1))) unsigned char*)ld(23); }
; __device__ __forceinline__ unsigned pk2(float lo, float hi) { return cvtpk(lo, hi); }
; #define LDS_WAIT() asm volatile("s_waitcnt lgkmcnt(0)" ::: "memory")
; template <bool UPMAP>
; __device__ __forceinline__ void transpose_item(const float* W, int K, int N, bf16* WT, float* scr, int item, int lane) {
;     const int nblk = N / 32, kb = item / nblk, nb = item % nblk, k0 = 64 * kb, n0 = 32 * nb;
;     { f32x4 v[8];
; #pragma unroll
;       for (int i = 0; i < 8; ++i) v[i] = *(const f32x4*)(W + (size_t)(k0 + 8 * i + (lane >> 3)) * N + n0 + 4 * (lane & 7));
; #pragma unroll
;       for (int i = 0; i < 8; ++i) { float* d = scr + (8 * i + (lane >> 3)) * 33 + 4 * (lane & 7); d[0] = v[i][0]; d[1] = v[i][1]; d[2] = v[i][2]; d[3] = v[i][3]; } }
;     LDS_WAIT();
;     const int c = lane & 7;
; #pragma unroll
;     for (int j = 0; j < 4; ++j) { const int n = (lane >> 3) + 8 * j; const float* s = scr + (8 * c) * 33 + n;
;         v4u o; o.x = pk2(s[0 * 33], s[1 * 33]); o.y = pk2(s[2 * 33], s[3 * 33]); o.z = pk2(s[4 * 33], s[5 * 33]); o.w = pk2(s[6 * 33], s[7 * 33]);
;         const int nsrc = n0 + n; int nrow = nsrc;
;         if (UPMAP) { const int bj = nsrc / 2816, chn = nsrc - bj * 2816; nrow = (chn >> 7) * 256 + bj * 128 + (chn & 127); }
;         *(v4u*)(WT + (size_t)nrow * K + k0 + 8 * c) = o; }
;     LDS_WAIT();
; template <int PART>
; __device__ __forceinline__ void prologue(const KPD& kp, unsigned char* lds, int tid, int lane, int wave) {
;     ...
;         if (r < I_OUT) { transpose_item<false>(kp.in(I_WOUT) + (size_t)l * D * D, D, D, (bf16*)(ws + WS_WOUT) + (size_t)l * D * D, scr, r, lane); continue; } r -= I_OUT;
.LBB0_97:
	s_andn2_b64 vcc, exec, s[4:5]
	s_cbranch_vccnz .LBB0_99
	v_mov_b32_e32 v26, 0x26480
	ds_read_b64 v[26:27], v26
	s_ashr_i32 s3, s2, 31
	s_lshl_b64 s[4:5], s[2:3], 22
	v_lshlrev_b32_e32 v34, 2, v2
	s_waitcnt lgkmcnt(0)
	v_readfirstlane_b32 s20, v26
	v_readfirstlane_b32 s19, v27
	s_add_u32 s20, s20, s4
	s_addc_u32 s19, s19, s5
	s_lshl_b64 s[4:5], s[2:3], 21
	s_add_u32 s21, s11, s4
	s_addc_u32 s22, s12, s5
	s_add_i32 s3, s18, 0xfbf0
	s_bfe_u32 s23, s3, 0xb0005
	s_lshl_b32 s3, s3, 5
	s_and_b32 s3, s3, 0x3e0
	s_lshl_b32 s4, s3, 2
	s_add_u32 s4, s20, s4
	s_addc_u32 s5, s19, 0
	v_lshl_add_u64 v[26:27], s[4:5], 0, v[34:35]
	v_lshl_or_b32 v34, s23, 18, v10
	v_lshl_add_u64 v[36:37], v[26:27], 0, v[34:35]
	s_mov_b32 s4, 0x8000
	v_add_co_u32_e32 v30, vcc, s4, v36
	s_mov_b32 s4, 0x10000
	s_nop 0
	v_addc_co_u32_e32 v31, vcc, 0, v37, vcc
	v_add_co_u32_e32 v42, vcc, s4, v36
	s_mov_b32 s4, 0x18000
	s_nop 0
	v_addc_co_u32_e32 v43, vcc, 0, v37, vcc
	v_add_co_u32_e32 v46, vcc, s4, v36
	s_mov_b32 s4, 0x20000
	s_nop 0
	v_addc_co_u32_e32 v47, vcc, 0, v37, vcc
	v_add_co_u32_e32 v50, vcc, s4, v36
	s_mov_b32 s4, 0x28000
	s_nop 0
	v_addc_co_u32_e32 v51, vcc, 0, v37, vcc
	v_add_co_u32_e32 v54, vcc, s4, v36
	global_load_dwordx4 v[26:29], v[36:37], off
	s_nop 0
	global_load_dwordx4 v[30:33], v[30:31], off
	v_addc_co_u32_e32 v55, vcc, 0, v37, vcc
	global_load_dwordx4 v[42:45], v[42:43], off
	s_nop 0
	global_load_dwordx4 v[46:49], v[46:47], off
	s_nop 0
	global_load_dwordx4 v[50:53], v[50:51], off
	s_nop 0
	global_load_dwordx4 v[54:57], v[54:55], off
	s_mov_b32 s4, 0x30000
	v_add_co_u32_e32 v58, vcc, s4, v36
	s_mov_b32 s4, 0x38000
	s_nop 0
	v_addc_co_u32_e32 v59, vcc, 0, v37, vcc
	global_load_dwordx4 v[58:61], v[58:59], off
	v_add_co_u32_e32 v36, vcc, s4, v36
	s_lshl_b32 s4, s23, 7
	s_nop 0
	v_addc_co_u32_e32 v37, vcc, 0, v37, vcc
	global_load_dwordx4 v[62:65], v[36:37], off
	s_add_u32 s4, s21, s4
	v_or_b32_e32 v38, s3, v5
	s_addc_u32 s5, s22, 0
	v_lshlrev_b32_e32 v34, 1, v4
	v_lshl_add_u64 v[36:37], s[4:5], 0, v[34:35]
	v_lshlrev_b32_e32 v34, 11, v38
	v_lshl_add_u64 v[66:67], v[36:37], 0, v[34:35]
	v_or_b32_e32 v39, s3, v6
	v_lshlrev_b32_e32 v34, 11, v39
	v_lshl_add_u64 v[68:69], v[36:37], 0, v[34:35]
	s_waitcnt vmcnt(7)
	ds_write2_b32 v11, v26, v27 offset1:1
	ds_write2_b32 v11, v28, v29 offset0:2 offset1:3
	s_waitcnt vmcnt(6)
	ds_write2_b32 v12, v30, v31 offset1:1
	ds_write2_b32 v13, v32, v33 offset1:1
	s_waitcnt vmcnt(5)
	ds_write2_b32 v14, v42, v43 offset1:1
	ds_write2_b32 v15, v44, v45 offset1:1
	s_waitcnt vmcnt(4)
	ds_write2_b32 v16, v46, v47 offset1:1
	ds_write2_b32 v17, v48, v49 offset1:1
	s_waitcnt vmcnt(3)
	ds_write2_b32 v18, v50, v51 offset1:1
	ds_write2_b32 v19, v52, v53 offset1:1
	s_waitcnt vmcnt(2)
	ds_write2_b32 v20, v54, v55 offset1:1
	ds_write2_b32 v21, v56, v57 offset1:1
	s_waitcnt vmcnt(1)
	ds_write2_b32 v22, v58, v59 offset1:1
	ds_write2_b32 v23, v60, v61 offset1:1
	s_waitcnt vmcnt(0)
	ds_write2_b32 v24, v62, v63 offset1:1
	ds_write2_b32 v25, v64, v65 offset1:1
	s_waitcnt lgkmcnt(0)
	ds_read2_b32 v[30:31], v9 offset0:33 offset1:41
	ds_read2_b32 v[32:33], v9 offset1:8
	ds_read2_b32 v[42:43], v9 offset0:66 offset1:74
	ds_read2_b32 v[44:45], v9 offset0:99 offset1:107
	ds_read2_b32 v[46:47], v9 offset0:132 offset1:140
	ds_read2_b32 v[48:49], v9 offset0:165 offset1:173
	ds_read2_b32 v[50:51], v9 offset0:198 offset1:206
	ds_read2_b32 v[52:53], v9 offset0:231 offset1:239
	ds_read2_b32 v[54:55], v9 offset0:16 offset1:24
	ds_read2_b32 v[56:57], v9 offset0:49 offset1:57
	ds_read2_b32 v[58:59], v9 offset0:82 offset1:90
	ds_read2_b32 v[60:61], v9 offset0:115 offset1:123
	ds_read2_b32 v[62:63], v9 offset0:148 offset1:156
	s_waitcnt lgkmcnt(11)
	v_cvt_pk_bf16_f32 v26, v32, v30
	s_waitcnt lgkmcnt(9)
	v_cvt_pk_bf16_f32 v27, v42, v44
	s_waitcnt lgkmcnt(7)
	v_cvt_pk_bf16_f32 v28, v46, v48
	s_waitcnt lgkmcnt(5)
	v_cvt_pk_bf16_f32 v29, v50, v52
	global_store_dwordx4 v[66:67], v[26:29], off sc1 nt
	v_cvt_pk_bf16_f32 v30, v33, v31
	v_cvt_pk_bf16_f32 v31, v43, v45
	v_cvt_pk_bf16_f32 v32, v47, v49
	ds_read2_b32 v[42:43], v9 offset0:181 offset1:189
	ds_read2_b32 v[44:45], v9 offset0:214 offset1:222
	ds_read2_b32 v[46:47], v9 offset0:247 offset1:255
	v_cvt_pk_bf16_f32 v33, v51, v53
	global_store_dwordx4 v[68:69], v[30:33], off sc1 nt
	s_waitcnt lgkmcnt(6)
	v_cvt_pk_bf16_f32 v26, v54, v56
	s_waitcnt lgkmcnt(4)
	v_cvt_pk_bf16_f32 v27, v58, v60
	s_waitcnt lgkmcnt(2)
	v_cvt_pk_bf16_f32 v28, v62, v42
	s_waitcnt lgkmcnt(0)
	v_cvt_pk_bf16_f32 v29, v44, v46
	v_or_b32_e32 v30, s3, v7
	v_lshlrev_b32_e32 v34, 11, v30
	v_lshl_add_u64 v[30:31], v[36:37], 0, v[34:35]
	global_store_dwordx4 v[30:31], v[26:29], off sc1 nt
	v_or_b32_e32 v30, s3, v8
	v_lshlrev_b32_e32 v34, 11, v30
	v_lshl_add_u64 v[30:31], v[36:37], 0, v[34:35]
	v_cvt_pk_bf16_f32 v26, v55, v57
	v_cvt_pk_bf16_f32 v27, v59, v61
	v_cvt_pk_bf16_f32 v28, v63, v43
	v_cvt_pk_bf16_f32 v29, v45, v47
	global_store_dwordx4 v[30:31], v[26:29], off sc1 nt
	s_waitcnt lgkmcnt(0)

;     __device__ __forceinline__ const float* in(int i) const { return (const float*)(const __attribute__((address_space(1))) float*)ld(i); }
;     __device__ __forceinline__ unsigned char* ws() const { return (unsigned char*)(__attribute__((address_space(1))) unsigned char*)ld(23); }
; __device__ __forceinline__ unsigned pk2(float lo, float hi) { return cvtpk(lo, hi); }
; #define LDS_WAIT() asm volatile("s_waitcnt lgkmcnt(0)" ::: "memory")
; template <bool UPMAP>
; __device__ __forceinline__ void transpose_item(const float* W, int K, int N, bf16* WT, float* scr, int item, int lane) {
;     const int nblk = N / 32, kb = item / nblk, nb = item % nblk, k0 = 64 * kb, n0 = 32 * nb;
;     { f32x4 v[8];
; #pragma unroll
;       for (int i = 0; i < 8; ++i) v[i] = *(const f32x4*)(W + (size_t)(k0 + 8 * i + (lane >> 3)) * N + n0 + 4 * (lane & 7));
; #pragma unroll
;       for (int i = 0; i < 8; ++i) { float* d = scr + (8 * i + (lane >> 3)) * 33 + 4 * (lane & 7); d[0] = v[i][0]; d[1] = v[i][1]; d[2] = v[i][2]; d[3] = v[i][3]; } }
;     LDS_WAIT();
;     const int c = lane & 7;
; #pragma unroll
;     for (int j = 0; j < 4; ++j) { const int n = (lane >> 3) + 8 * j; const float* s = scr + (8 * c) * 33 + n;
;         v4u o; o.x = pk2(s[0 * 33], s[1 * 33]); o.y = pk2(s[2 * 33], s[3 * 33]); o.z = pk2(s[4 * 33], s[5 * 33]); o.w = pk2(s[6 * 33], s[7 * 33]);
;         const int nsrc = n0 + n; int nrow = nsrc;
;         if (UPMAP) { const int bj = nsrc / 2816, chn = nsrc - bj * 2816; nrow = (chn >> 7) * 256 + bj * 128 + (chn & 127); }
;         *(v4u*)(WT + (size_t)nrow * K + k0 + 8 * c) = o; }
;     LDS_WAIT();
; template <int PART>
; __device__ __forceinline__ void prologue(const KPD& kp, unsigned char* lds, int tid, int lane, int wave) {
;     ...
;         if (r < I_IN) { transpose_item<false>(kp.in(I_WIN) + (size_t)l * D * INW, D, INW, (bf16*)(ws + WS_WIN) + (size_t)l * INP * D, scr, r, lane); continue; } r -= I_IN;
.LBB0_101:
	v_mov_b32_e32 v26, 0x26438
	ds_read_b64 v[26:27], v26
	s_mul_i32 s4, s2, 0x820000
	s_mul_hi_i32 s3, s2, 0x820000
	s_mul_hi_i32 s5, s2, 0x480000
	s_mul_i32 s2, s2, 0x480000
	s_waitcnt lgkmcnt(0)
	v_readfirstlane_b32 s20, v26
	v_readfirstlane_b32 s19, v27
	s_add_u32 s20, s20, s4
	s_addc_u32 s21, s19, s3
	s_add_u32 s22, s13, s2
	s_mul_i32 s2, s18, 0xfc1
	s_addc_u32 s23, s16, s5
	s_lshr_b32 s3, s2, 31
	s_ashr_i32 s2, s2, 18
	s_add_i32 s2, s2, s3
	s_mul_i32 s3, s2, 0x41
	s_sub_i32 s3, s18, s3
	s_sext_i32_i16 s3, s3
	s_lshl_b32 s4, s2, 6
	s_lshl_b32 s2, s3, 5
	s_ashr_i32 s3, s2, 31
	s_lshl_b64 s[18:19], s[2:3], 2
	v_or_b32_e32 v28, s4, v5
	s_add_u32 s18, s20, s18
	s_addc_u32 s19, s21, s19
	v_lshlrev_b32_e32 v34, 2, v2
	v_mul_i32_i24_e32 v28, 0x820, v28
	v_lshl_add_u64 v[26:27], s[18:19], 0, v[34:35]
	v_ashrrev_i32_e32 v29, 31, v28
	v_lshl_add_u64 v[36:37], v[28:29], 2, v[26:27]
	s_mov_b32 s3, 0x10000
	v_add_co_u32_e32 v30, vcc, s3, v36
	s_mov_b32 s3, 0x20000
	s_nop 0
	v_addc_co_u32_e32 v31, vcc, 0, v37, vcc
	v_add_co_u32_e32 v42, vcc, s3, v36
	s_mov_b32 s3, 0x30000
	s_nop 0
	v_addc_co_u32_e32 v43, vcc, 0, v37, vcc
	v_add_co_u32_e32 v46, vcc, s3, v36
	s_mov_b32 s3, 0x41000
	s_nop 0
	v_addc_co_u32_e32 v47, vcc, 0, v37, vcc
	v_add_co_u32_e32 v50, vcc, s3, v36
	s_mov_b32 s3, 0x51000
	s_nop 0
	v_addc_co_u32_e32 v51, vcc, 0, v37, vcc
	v_add_co_u32_e32 v54, vcc, s3, v36
	global_load_dwordx4 v[26:29], v[36:37], off
	s_nop 0
	global_load_dwordx4 v[30:33], v[30:31], off offset:1024
	v_addc_co_u32_e32 v55, vcc, 0, v37, vcc
	global_load_dwordx4 v[42:45], v[42:43], off offset:2048
	s_nop 0
	global_load_dwordx4 v[46:49], v[46:47], off offset:3072
	s_nop 0
	global_load_dwordx4 v[50:53], v[50:51], off
	s_nop 0
	global_load_dwordx4 v[54:57], v[54:55], off offset:1024
	s_mov_b32 s3, 0x61000
	v_add_co_u32_e32 v58, vcc, s3, v36
	s_mov_b32 s3, 0x71000
	s_nop 0
	v_addc_co_u32_e32 v59, vcc, 0, v37, vcc
	global_load_dwordx4 v[58:61], v[58:59], off offset:2048
	v_add_co_u32_e32 v36, vcc, s3, v36
	s_ashr_i32 s5, s4, 31
	s_nop 0
	v_addc_co_u32_e32 v37, vcc, 0, v37, vcc
	global_load_dwordx4 v[62:65], v[36:37], off offset:3072
	s_lshl_b64 s[4:5], s[4:5], 1
	v_or_b32_e32 v36, s2, v5
	s_add_u32 s4, s22, s4
	v_ashrrev_i32_e32 v37, 31, v36
	v_lshlrev_b32_e32 v34, 1, v4
	s_addc_u32 s5, s23, s5
	v_or_b32_e32 v66, s2, v6
	v_lshlrev_b64 v[36:37], 11, v[36:37]
	v_lshl_add_u64 v[68:69], s[4:5], 0, v[34:35]
	v_lshl_add_u64 v[36:37], v[68:69], 0, v[36:37]
	v_ashrrev_i32_e32 v67, 31, v66
	s_waitcnt vmcnt(7)
	ds_write2_b32 v11, v26, v27 offset1:1
	ds_write2_b32 v11, v28, v29 offset0:2 offset1:3
	s_waitcnt vmcnt(6)
	ds_write2_b32 v12, v30, v31 offset1:1
	ds_write2_b32 v13, v32, v33 offset1:1
	s_waitcnt vmcnt(5)
	ds_write2_b32 v14, v42, v43 offset1:1
	ds_write2_b32 v15, v44, v45 offset1:1
	s_waitcnt vmcnt(4)
	ds_write2_b32 v16, v46, v47 offset1:1
	ds_write2_b32 v17, v48, v49 offset1:1
	s_waitcnt vmcnt(3)
	ds_write2_b32 v18, v50, v51 offset1:1
	ds_write2_b32 v19, v52, v53 offset1:1
	s_waitcnt vmcnt(2)
	ds_write2_b32 v20, v54, v55 offset1:1
	ds_write2_b32 v21, v56, v57 offset1:1
	s_waitcnt vmcnt(1)
	ds_write2_b32 v22, v58, v59 offset1:1
	ds_write2_b32 v23, v60, v61 offset1:1
	s_waitcnt vmcnt(0)
	ds_write2_b32 v24, v62, v63 offset1:1
	ds_write2_b32 v25, v64, v65 offset1:1
	s_waitcnt lgkmcnt(0)
	ds_read2_b32 v[30:31], v9 offset0:33 offset1:41
	ds_read2_b32 v[32:33], v9 offset1:8
	ds_read2_b32 v[42:43], v9 offset0:66 offset1:74
	ds_read2_b32 v[44:45], v9 offset0:99 offset1:107
	ds_read2_b32 v[46:47], v9 offset0:132 offset1:140
	ds_read2_b32 v[48:49], v9 offset0:165 offset1:173
	ds_read2_b32 v[50:51], v9 offset0:198 offset1:206
	ds_read2_b32 v[52:53], v9 offset0:231 offset1:239
	s_waitcnt lgkmcnt(6)
	v_cvt_pk_bf16_f32 v26, v32, v30
	s_waitcnt lgkmcnt(4)
	v_cvt_pk_bf16_f32 v27, v42, v44
	s_waitcnt lgkmcnt(2)
	v_cvt_pk_bf16_f32 v28, v46, v48
	s_waitcnt lgkmcnt(0)
	v_cvt_pk_bf16_f32 v29, v50, v52
	global_store_dwordx4 v[36:37], v[26:29], off sc1 nt
	v_cvt_pk_bf16_f32 v30, v33, v31
	v_cvt_pk_bf16_f32 v31, v43, v45
	v_cvt_pk_bf16_f32 v32, v47, v49
	v_cvt_pk_bf16_f32 v33, v51, v53
	ds_read2_b32 v[36:37], v9 offset0:16 offset1:24
	ds_read2_b32 v[42:43], v9 offset0:49 offset1:57
	ds_read2_b32 v[44:45], v9 offset0:82 offset1:90
	ds_read2_b32 v[46:47], v9 offset0:115 offset1:123
	ds_read2_b32 v[48:49], v9 offset0:148 offset1:156
	ds_read2_b32 v[50:51], v9 offset0:181 offset1:189
	ds_read2_b32 v[52:53], v9 offset0:214 offset1:222
	ds_read2_b32 v[54:55], v9 offset0:247 offset1:255
	v_lshlrev_b64 v[26:27], 11, v[66:67]
	v_lshl_add_u64 v[26:27], v[68:69], 0, v[26:27]
	global_store_dwordx4 v[26:27], v[30:33], off sc1 nt
	s_waitcnt lgkmcnt(6)
	v_cvt_pk_bf16_f32 v26, v36, v42
	s_waitcnt lgkmcnt(4)
	v_cvt_pk_bf16_f32 v27, v44, v46
	s_waitcnt lgkmcnt(2)
	v_cvt_pk_bf16_f32 v28, v48, v50
	s_waitcnt lgkmcnt(0)
	v_cvt_pk_bf16_f32 v29, v52, v54
	v_or_b32_e32 v30, s2, v7
	v_ashrrev_i32_e32 v31, 31, v30
	v_lshlrev_b64 v[30:31], 11, v[30:31]
	v_lshl_add_u64 v[30:31], v[68:69], 0, v[30:31]
	global_store_dwordx4 v[30:31], v[26:29], off sc1 nt
	v_or_b32_e32 v30, s2, v8
	v_ashrrev_i32_e32 v31, 31, v30
	v_lshlrev_b64 v[30:31], 11, v[30:31]
	v_lshl_add_u64 v[30:31], v[68:69], 0, v[30:31]
	v_cvt_pk_bf16_f32 v26, v37, v43
	v_cvt_pk_bf16_f32 v27, v45, v47
	v_cvt_pk_bf16_f32 v28, v49, v51
	v_cvt_pk_bf16_f32 v29, v53, v55
	global_store_dwordx4 v[30:31], v[26:29], off sc1 nt
	s_waitcnt lgkmcnt(0)
	s_branch .LBB0_89

;     __device__ __forceinline__ unsigned char* ws() const { return (unsigned char*)(__attribute__((address_space(1))) unsigned char*)ld(23); }
; template <int PART>
; __device__ __forceinline__ void prologue(const KPD& kp, unsigned char* lds, int tid, int lane, int wave) {
;     ...
;     { const int gt = blockIdx.x * 512 + tid, NT = gridDim.x * 512; constexpr int PADV = (INP - INW) * D * 2 / 16;
;       for (int i = gt; i < 2 * PADV; i += NT) { const int l = i / PADV, r = i % PADV; *((v4u*)((bf16*)(ws + WS_WIN) + (size_t)l * INP * D + (size_t)INW * D) + r) = (v4u){0u, 0u, 0u, 0u}; } }
.LBB0_106:
	s_mov_b32 s6, 0x92492493
	v_mul_hi_i32 v3, v2, s6
	v_add_u32_e32 v3, v3, v2
	v_lshrrev_b32_e32 v4, 31, v3
	v_ashrrev_i32_e32 v3, 14, v3
	v_add_u32_e32 v3, v3, v4
	v_mul_i32_i24_e32 v5, 0x7000, v3
	v_mul_i32_i24_e32 v4, 0x900, v3
	v_sub_u32_e32 v6, v2, v5
	v_ashrrev_i32_e32 v5, 31, v4
	v_lshlrev_b64 v[4:5], 11, v[4:5]
	v_add_u32_e32 v2, s80, v2
	v_ashrrev_i32_e32 v7, 31, v6
	s_mov_b32 s6, 0xdfff
	v_lshl_add_u64 v[4:5], s[0:1], 0, v[4:5]
	v_cmp_lt_i32_e32 vcc, s6, v2
	v_lshl_add_u64 v[4:5], v[6:7], 4, v[4:5]
	s_or_b64 s[4:5], vcc, s[4:5]
	v_add_co_u32_e32 v4, vcc, 0x610000, v4
	s_nop 1
	v_addc_co_u32_e32 v5, vcc, 0, v5, vcc
	global_store_dwordx4 v[4:5], v[70:73], off sc1 nt
	s_andn2_b64 exec, exec, s[4:5]
	s_cbranch_execnz .LBB0_106

; template <int NR>
; __device__ __forceinline__ void norm_group(int m0, const float* src_lat, const float* src_ctx, bf16* H, const float* gain, const float* mod, int shoff, int scoff, int lane, const float* part, float* ctx_out) {
;     const float* xr = (m0 < MLAT) ? src_lat + (size_t)m0 * D : src_ctx + (size_t)(m0 - MLAT) * D;
;     const int b = (m0 < MLAT) ? (m0 >> 13) : 4;
;     f32x4 v[NR][4]; float rstd[NR];
; #pragma unroll
;     for (int i = 0; i < NR; ++i)
; #pragma unroll
;         for (int j = 0; j < 4; ++j) v[i][j] = *((const f32x4*)(xr + (size_t)i * D) + lane + 64 * j);
;     if (part && m0 >= MLAT) {
; #pragma unroll
;         for (int i = 0; i < NR; ++i)
; #pragma unroll
;             for (int j = 0; j < 4; ++j) { const size_t o = (size_t)(m0 - MLAT + i) * D + 4 * (lane + 64 * j);
;                 const f32x4 p0 = *(const f32x4*)(part + o), p1 = *(const f32x4*)(part + (size_t)MCTX * D + o), p2 = *(const f32x4*)(part + (size_t)2 * MCTX * D + o), p3 = *(const f32x4*)(part + (size_t)3 * MCTX * D + o);
;                 v[i][j] = v[i][j] + ((p0 + p1) + (p2 + p3)); *(f32x4*)(ctx_out + o) = v[i][j]; }
;     }
; #pragma unroll
;     for (int i = 0; i < NR; ++i) { float s = 0.f;
; #pragma unroll
;         for (int j = 0; j < 4; ++j) s += (v[i][j].x * v[i][j].x + v[i][j].y * v[i][j].y) + (v[i][j].z * v[i][j].z + v[i][j].w * v[i][j].w);
;         rstd[i] = 1.0f / sqrtf(wave_sum(s) * (1.f / D) + EPS); }
.LBB0_110:
	s_ashr_i32 s9, s8, 31
	s_lshl_b64 s[0:1], s[8:9], 12
	v_lshl_add_u64 v[6:7], v[36:37], 0, s[0:1]
	global_load_dwordx4 v[70:73], v[6:7], off
	global_load_dwordx4 v[54:57], v[6:7], off offset:1024
	global_load_dwordx4 v[30:33], v[6:7], off offset:2048
	global_load_dwordx4 v[14:17], v[6:7], off offset:3072
	v_add_co_u32_e32 v2, vcc, 0x1000, v6
	s_waitcnt vmcnt(3)
	v_pk_mul_f32 v[96:97], v[72:73], v[72:73]
	v_addc_co_u32_e32 v3, vcc, 0, v7, vcc
	global_load_dwordx4 v[66:69], v[2:3], off
	global_load_dwordx4 v[46:49], v[2:3], off offset:1024
	global_load_dwordx4 v[18:21], v[2:3], off offset:2048
	s_nop 0
	global_load_dwordx4 v[2:5], v[2:3], off offset:3072
	v_pk_mul_f32 v[98:99], v[70:71], v[70:71]
	s_waitcnt vmcnt(4)
	v_mul_f32_e32 v38, v14, v14
	v_pk_mov_b32 v[100:101], v[98:99], v[96:97] op_sel:[1,0]
	v_mov_b32_e32 v99, v97
	v_pk_add_f32 v[96:97], v[100:101], v[98:99]
	v_pk_mul_f32 v[98:99], v[56:57], v[56:57]
	v_pk_mul_f32 v[100:101], v[54:55], v[54:55]
	v_mul_f32_e32 v39, v15, v15
	v_pk_mov_b32 v[102:103], v[100:101], v[98:99] op_sel:[1,0]
	v_mov_b32_e32 v101, v99
	v_pk_add_f32 v[98:99], v[102:103], v[100:101]
	v_pk_add_f32 v[96:97], v[96:97], v[96:97] op_sel:[0,1] op_sel_hi:[1,0]
	v_pk_add_f32 v[98:99], v[98:99], v[98:99] op_sel:[0,1] op_sel_hi:[1,0]
	v_mov_b32_e32 v97, v38
	v_mov_b32_e32 v99, v39
	v_mul_f32_e32 v80, v31, v31
	v_pk_add_f32 v[96:97], v[96:97], v[98:99]
	v_pk_fma_f32 v[98:99], v[30:31], v[30:31], v[80:81] op_sel_hi:[1,1,0]
	v_mul_f32_e32 v80, v33, v33
	v_mul_f32_e32 v40, v16, v16
	v_mul_f32_e32 v41, v17, v17
	v_pk_fma_f32 v[100:101], v[32:33], v[32:33], v[80:81] op_sel_hi:[1,1,0]
	v_mov_b32_e32 v99, v40
	v_mov_b32_e32 v101, v41
	v_pk_add_f32 v[98:99], v[98:99], v[100:101]
	v_add_co_u32_e32 v8, vcc, s96, v6
	v_pk_add_f32 v[96:97], v[96:97], v[98:99]
	s_nop 0
	v_addc_co_u32_e32 v9, vcc, 0, v7, vcc
	v_add_f32_e32 v38, v96, v97
	ds_bpermute_b32 v39, v89, v38
	v_add_co_u32_e32 v6, vcc, s87, v6
	s_waitcnt lgkmcnt(0)
	v_add_f32_e32 v38, v38, v39
	ds_bpermute_b32 v39, v90, v38
	v_addc_co_u32_e32 v7, vcc, 0, v7, vcc
	global_load_dwordx4 v[62:65], v[6:7], off offset:-4096
	global_load_dwordx4 v[50:53], v[8:9], off offset:1024
	global_load_dwordx4 v[26:29], v[8:9], off offset:2048
	global_load_dwordx4 v[10:13], v[8:9], off offset:3072
	global_load_dwordx4 v[58:61], v[6:7], off
	global_load_dwordx4 v[42:45], v[6:7], off offset:1024
	global_load_dwordx4 v[22:25], v[6:7], off offset:2048
	s_nop 0
	global_load_dwordx4 v[6:9], v[6:7], off offset:3072
	s_waitcnt lgkmcnt(0)
	v_add_f32_e32 v38, v38, v39
	ds_bpermute_b32 v39, v91, v38
	s_waitcnt lgkmcnt(0)
	v_add_f32_e32 v38, v38, v39
	ds_bpermute_b32 v39, v92, v38
	s_waitcnt lgkmcnt(0)
	v_add_f32_e32 v38, v38, v39
	ds_bpermute_b32 v39, v93, v38
	s_waitcnt lgkmcnt(0)
	v_add_f32_e32 v38, v38, v39
	ds_bpermute_b32 v39, v94, v38
	s_waitcnt lgkmcnt(0)
	v_add_f32_e32 v38, v38, v39
	v_fmamk_f32 v38, v38, 0x3a800000, v205
	v_cmp_gt_f32_e32 vcc, s88, v38
	v_mul_f32_e32 v39, 0x4f800000, v38
	s_waitcnt vmcnt(11)
	v_pk_mul_f32 v[96:97], v[68:69], v[68:69]
	v_cndmask_b32_e32 v38, v38, v39, vcc
	v_sqrt_f32_e32 v39, v38
	v_pk_mul_f32 v[98:99], v[66:67], v[66:67]
	s_waitcnt vmcnt(9)
	v_mul_f32_e32 v82, v19, v19
	v_pk_mov_b32 v[100:101], v[98:99], v[96:97] op_sel:[1,0]
	v_add_u32_e32 v40, -1, v39
	v_fma_f32 v41, -v40, v39, v38
	v_cmp_ge_f32_e64 s[0:1], 0, v41
	v_add_u32_e32 v41, 1, v39
	v_mov_b32_e32 v99, v97
	v_cndmask_b32_e64 v40, v39, v40, s[0:1]
	v_fma_f32 v39, -v41, v39, v38
	v_cmp_lt_f32_e64 s[0:1], 0, v39
	v_pk_add_f32 v[96:97], v[100:101], v[98:99]
	v_pk_mul_f32 v[98:99], v[48:49], v[48:49]
	v_cndmask_b32_e64 v39, v40, v41, s[0:1]
	v_mul_f32_e32 v40, 0x37800000, v39
	v_cndmask_b32_e32 v39, v39, v40, vcc
	v_cmp_class_f32_e32 vcc, v38, v206
	v_pk_mul_f32 v[100:101], v[46:47], v[46:47]
	v_pk_add_f32 v[96:97], v[96:97], v[96:97] op_sel:[0,1] op_sel_hi:[1,0]
	v_cndmask_b32_e32 v38, v39, v38, vcc
	v_div_scale_f32 v39, s[0:1], v38, v38, 1.0
	v_rcp_f32_e32 v40, v39
	v_pk_mov_b32 v[102:103], v[100:101], v[98:99] op_sel:[1,0]
	v_mov_b32_e32 v101, v99
	v_pk_add_f32 v[98:99], v[102:103], v[100:101]
	v_fma_f32 v41, -v39, v40, 1.0
	v_fmac_f32_e32 v40, v41, v40
	v_div_scale_f32 v41, vcc, 1.0, v38, 1.0
	v_mul_f32_e32 v77, v41, v40
	v_fma_f32 v80, -v39, v77, v41
	v_fmac_f32_e32 v77, v80, v40
	v_fma_f32 v39, -v39, v77, v41
	v_div_fmas_f32 v39, v39, v40, v77
	v_div_fixup_f32 v80, v39, v38, 1.0
	s_waitcnt vmcnt(8)
	v_mul_f32_e32 v38, v2, v2
	v_mul_f32_e32 v39, v3, v3
	v_pk_add_f32 v[98:99], v[98:99], v[98:99] op_sel:[0,1] op_sel_hi:[1,0]
	v_mov_b32_e32 v97, v38
	v_mov_b32_e32 v99, v39
	v_pk_add_f32 v[96:97], v[96:97], v[98:99]
	v_pk_fma_f32 v[98:99], v[18:19], v[18:19], v[82:83] op_sel_hi:[1,1,0]
	v_mul_f32_e32 v82, v21, v21
	v_mul_f32_e32 v40, v4, v4
	v_mul_f32_e32 v41, v5, v5
	v_pk_fma_f32 v[100:101], v[20:21], v[20:21], v[82:83] op_sel_hi:[1,1,0]
	v_mov_b32_e32 v99, v40
	v_mov_b32_e32 v101, v41
	v_pk_add_f32 v[98:99], v[98:99], v[100:101]
	s_waitcnt vmcnt(5)
	v_mul_f32_e32 v84, v27, v27
	v_pk_add_f32 v[96:97], v[96:97], v[98:99]
	v_pk_mul_f32 v[98:99], v[62:63], v[62:63]
	v_add_f32_e32 v38, v96, v97
	ds_bpermute_b32 v39, v89, v38
	v_pk_mul_f32 v[96:97], v[64:65], v[64:65]
	s_waitcnt vmcnt(1)
	v_mul_f32_e32 v86, v23, v23
	v_pk_mov_b32 v[100:101], v[98:99], v[96:97] op_sel:[1,0]
	v_mov_b32_e32 v99, v97
	s_waitcnt lgkmcnt(0)
	v_add_f32_e32 v38, v38, v39
	ds_bpermute_b32 v39, v90, v38
	v_pk_add_f32 v[96:97], v[100:101], v[98:99]
	v_pk_mul_f32 v[98:99], v[52:53], v[52:53]
	v_pk_mul_f32 v[100:101], v[50:51], v[50:51]
	v_pk_add_f32 v[96:97], v[96:97], v[96:97] op_sel:[0,1] op_sel_hi:[1,0]
	s_waitcnt lgkmcnt(0)
; template <int NR>
; __device__ __forceinline__ void norm_group(int m0, const float* src_lat, const float* src_ctx, bf16* H, const float* gain, const float* mod, int shoff, int scoff, int lane, const float* part, float* ctx_out) {
;     ...
;     for (int i = 0; i < NR; ++i) { float s = 0.f;
; #pragma unroll
;         for (int j = 0; j < 4; ++j) s += (v[i][j].x * v[i][j].x + v[i][j].y * v[i][j].y) + (v[i][j].z * v[i][j].z + v[i][j].w * v[i][j].w);
;         rstd[i] = 1.0f / sqrtf(wave_sum(s) * (1.f / D) + EPS); }
	v_add_f32_e32 v38, v38, v39
	ds_bpermute_b32 v39, v91, v38
	v_pk_mov_b32 v[102:103], v[100:101], v[98:99] op_sel:[1,0]
	v_mov_b32_e32 v101, v99
	v_pk_add_f32 v[98:99], v[102:103], v[100:101]
	v_pk_mul_f32 v[70:71], v[70:71], v[80:81] op_sel_hi:[1,0]
	s_waitcnt lgkmcnt(0)
	v_add_f32_e32 v38, v38, v39
	ds_bpermute_b32 v39, v92, v38
	v_pk_add_f32 v[98:99], v[98:99], v[98:99] op_sel:[0,1] op_sel_hi:[1,0]
	v_pk_mul_f32 v[72:73], v[72:73], v[80:81] op_sel_hi:[1,0]
	v_pk_mul_f32 v[54:55], v[54:55], v[80:81] op_sel_hi:[1,0]
	v_pk_mul_f32 v[56:57], v[56:57], v[80:81] op_sel_hi:[1,0]
	s_waitcnt lgkmcnt(0)
	v_add_f32_e32 v38, v38, v39
	ds_bpermute_b32 v39, v93, v38
	v_pk_mul_f32 v[30:31], v[30:31], v[80:81] op_sel_hi:[1,0]
	v_pk_mul_f32 v[32:33], v[32:33], v[80:81] op_sel_hi:[1,0]
	v_pk_mul_f32 v[14:15], v[14:15], v[80:81] op_sel_hi:[1,0]
	v_pk_mul_f32 v[16:17], v[16:17], v[80:81] op_sel_hi:[1,0]
	s_waitcnt lgkmcnt(0)
	v_add_f32_e32 v38, v38, v39
	ds_bpermute_b32 v39, v94, v38
	s_waitcnt lgkmcnt(0)
	v_add_f32_e32 v38, v38, v39
	v_fmamk_f32 v38, v38, 0x3a800000, v205
	v_cmp_gt_f32_e32 vcc, s88, v38
	v_mul_f32_e32 v39, 0x4f800000, v38
	s_nop 0
	v_cndmask_b32_e32 v38, v38, v39, vcc
	v_sqrt_f32_e32 v39, v38
	s_nop 0
	v_add_u32_e32 v40, -1, v39
	v_fma_f32 v41, -v40, v39, v38
	v_cmp_ge_f32_e64 s[0:1], 0, v41
	v_add_u32_e32 v41, 1, v39
	s_nop 0
	v_cndmask_b32_e64 v40, v39, v40, s[0:1]
	v_fma_f32 v39, -v41, v39, v38
	v_cmp_lt_f32_e64 s[0:1], 0, v39
	s_nop 1
	v_cndmask_b32_e64 v39, v40, v41, s[0:1]
	v_mul_f32_e32 v40, 0x37800000, v39
	v_cndmask_b32_e32 v39, v39, v40, vcc
	v_cmp_class_f32_e32 vcc, v38, v206
	s_nop 1
	v_cndmask_b32_e32 v38, v39, v38, vcc
	v_div_scale_f32 v39, s[0:1], v38, v38, 1.0
	v_rcp_f32_e32 v40, v39
	s_nop 0
	v_fma_f32 v41, -v39, v40, 1.0
	v_fmac_f32_e32 v40, v41, v40
	v_div_scale_f32 v41, vcc, 1.0, v38, 1.0
	v_mul_f32_e32 v77, v41, v40
	v_fma_f32 v82, -v39, v77, v41
	v_fmac_f32_e32 v77, v82, v40
	v_fma_f32 v39, -v39, v77, v41
	v_div_fmas_f32 v39, v39, v40, v77
	v_div_fixup_f32 v82, v39, v38, 1.0
	v_mul_f32_e32 v38, v10, v10
	v_mul_f32_e32 v39, v11, v11
	v_mov_b32_e32 v97, v38
	v_mov_b32_e32 v99, v39
	v_pk_add_f32 v[96:97], v[96:97], v[98:99]
	v_pk_fma_f32 v[98:99], v[26:27], v[26:27], v[84:85] op_sel_hi:[1,1,0]
	v_mul_f32_e32 v84, v29, v29
	v_mul_f32_e32 v40, v12, v12
	v_mul_f32_e32 v41, v13, v13
	v_pk_fma_f32 v[100:101], v[28:29], v[28:29], v[84:85] op_sel_hi:[1,1,0]
	v_mov_b32_e32 v99, v40
	v_mov_b32_e32 v101, v41
	v_pk_add_f32 v[98:99], v[98:99], v[100:101]
	v_pk_mul_f32 v[66:67], v[66:67], v[82:83] op_sel_hi:[1,0]
	v_pk_add_f32 v[96:97], v[96:97], v[98:99]
	v_pk_mul_f32 v[98:99], v[58:59], v[58:59]
	v_add_f32_e32 v38, v96, v97
	ds_bpermute_b32 v39, v89, v38
	v_pk_mul_f32 v[96:97], v[60:61], v[60:61]
	v_pk_mul_f32 v[68:69], v[68:69], v[82:83] op_sel_hi:[1,0]
	v_pk_mov_b32 v[100:101], v[98:99], v[96:97] op_sel:[1,0]
	v_mov_b32_e32 v99, v97
	s_waitcnt lgkmcnt(0)
	v_add_f32_e32 v38, v38, v39
	ds_bpermute_b32 v39, v90, v38
	v_pk_add_f32 v[96:97], v[100:101], v[98:99]
	v_pk_mul_f32 v[98:99], v[44:45], v[44:45]
	v_pk_mul_f32 v[100:101], v[42:43], v[42:43]
	v_pk_add_f32 v[96:97], v[96:97], v[96:97] op_sel:[0,1] op_sel_hi:[1,0]
	s_waitcnt lgkmcnt(0)
	v_add_f32_e32 v38, v38, v39
	ds_bpermute_b32 v39, v91, v38
	v_pk_mov_b32 v[102:103], v[100:101], v[98:99] op_sel:[1,0]
	v_mov_b32_e32 v101, v99
	v_pk_add_f32 v[98:99], v[102:103], v[100:101]
	v_pk_mul_f32 v[46:47], v[46:47], v[82:83] op_sel_hi:[1,0]
	s_waitcnt lgkmcnt(0)
	v_add_f32_e32 v38, v38, v39
	ds_bpermute_b32 v39, v92, v38
	v_pk_add_f32 v[98:99], v[98:99], v[98:99] op_sel:[0,1] op_sel_hi:[1,0]
	v_pk_mul_f32 v[48:49], v[48:49], v[82:83] op_sel_hi:[1,0]
	v_pk_mul_f32 v[18:19], v[18:19], v[82:83] op_sel_hi:[1,0]
	v_pk_mul_f32 v[20:21], v[20:21], v[82:83] op_sel_hi:[1,0]
	s_waitcnt lgkmcnt(0)
	v_add_f32_e32 v38, v38, v39
	ds_bpermute_b32 v39, v93, v38
	v_pk_mul_f32 v[2:3], v[2:3], v[82:83] op_sel_hi:[1,0]
	v_pk_mul_f32 v[4:5], v[4:5], v[82:83] op_sel_hi:[1,0]
	s_waitcnt lgkmcnt(0)
	v_add_f32_e32 v38, v38, v39
	ds_bpermute_b32 v39, v94, v38
	s_waitcnt lgkmcnt(0)
	v_add_f32_e32 v38, v38, v39
	v_fmamk_f32 v38, v38, 0x3a800000, v205
	v_cmp_gt_f32_e32 vcc, s88, v38
	v_mul_f32_e32 v39, 0x4f800000, v38
	s_nop 0
	v_cndmask_b32_e32 v38, v38, v39, vcc
	v_sqrt_f32_e32 v39, v38
	s_nop 0
	v_add_u32_e32 v40, -1, v39
	v_fma_f32 v41, -v40, v39, v38
	v_cmp_ge_f32_e64 s[0:1], 0, v41
	v_add_u32_e32 v41, 1, v39
	s_nop 0
	v_cndmask_b32_e64 v40, v39, v40, s[0:1]
	v_fma_f32 v39, -v41, v39, v38
	v_cmp_lt_f32_e64 s[0:1], 0, v39
	s_nop 1
	v_cndmask_b32_e64 v39, v40, v41, s[0:1]
	v_mul_f32_e32 v40, 0x37800000, v39
	v_cndmask_b32_e32 v39, v39, v40, vcc
	v_cmp_class_f32_e32 vcc, v38, v206
	s_nop 1
	v_cndmask_b32_e32 v38, v39, v38, vcc
	v_div_scale_f32 v39, s[0:1], v38, v38, 1.0
	v_rcp_f32_e32 v40, v39
	s_nop 0
	v_fma_f32 v41, -v39, v40, 1.0
	v_fmac_f32_e32 v40, v41, v40
	v_div_scale_f32 v41, vcc, 1.0, v38, 1.0
	v_mul_f32_e32 v77, v41, v40
	v_fma_f32 v84, -v39, v77, v41
	v_fmac_f32_e32 v77, v84, v40
	v_fma_f32 v39, -v39, v77, v41
	v_div_fmas_f32 v39, v39, v40, v77
	v_div_fixup_f32 v84, v39, v38, 1.0
	s_waitcnt vmcnt(0)
	v_mul_f32_e32 v38, v6, v6
	v_mul_f32_e32 v39, v7, v7
	v_mov_b32_e32 v97, v38
	v_mov_b32_e32 v99, v39
	v_pk_add_f32 v[96:97], v[96:97], v[98:99]
	v_pk_fma_f32 v[98:99], v[22:23], v[22:23], v[86:87] op_sel_hi:[1,1,0]
	v_mul_f32_e32 v86, v25, v25
	v_mul_f32_e32 v40, v8, v8
	v_mul_f32_e32 v41, v9, v9
	v_pk_fma_f32 v[100:101], v[24:25], v[24:25], v[86:87] op_sel_hi:[1,1,0]
	v_mov_b32_e32 v99, v40
	v_mov_b32_e32 v101, v41
	v_pk_add_f32 v[98:99], v[98:99], v[100:101]
	v_pk_mul_f32 v[62:63], v[62:63], v[84:85] op_sel_hi:[1,0]
	v_pk_add_f32 v[96:97], v[96:97], v[98:99]
	v_pk_mul_f32 v[64:65], v[64:65], v[84:85] op_sel_hi:[1,0]
	v_add_f32_e32 v38, v96, v97
	ds_bpermute_b32 v39, v89, v38
	s_waitcnt lgkmcnt(0)
; __device__ __forceinline__ unsigned pk2(float lo, float hi) { return cvtpk(lo, hi); }
; template <int NR>
; __device__ __forceinline__ void norm_group(int m0, const float* src_lat, const float* src_ctx, bf16* H, const float* gain, const float* mod, int shoff, int scoff, int lane, const float* part, float* ctx_out) {
;     ...
;         rstd[i] = 1.0f / sqrtf(wave_sum(s) * (1.f / D) + EPS); }
;     const float* mr = mod + b * 6144;
; #pragma unroll
;     for (int j = 0; j < 4; ++j) { const int idx = 4 * (lane + 64 * j);
;         const f32x4 g = *(const f32x4*)(gain + idx), sc = *(const f32x4*)(mr + scoff + idx), sh = *(const f32x4*)(mr + shoff + idx);
;         const f32x4 gs = g * (1.f + sc);
; #pragma unroll
;         for (int i = 0; i < NR; ++i) { const f32x4 y = v[i][j] * rstd[i] * gs + sh;
;             v2u o; o.x = pk2(y.x, y.y); o.y = pk2(y.z, y.w);
;             *(v2u*)(H + (size_t)(m0 + i) * D + idx) = o; } }
	v_add_f32_e32 v38, v38, v39
	ds_bpermute_b32 v39, v90, v38
	s_waitcnt lgkmcnt(0)
	v_add_f32_e32 v38, v38, v39
	ds_bpermute_b32 v39, v91, v38
	s_waitcnt lgkmcnt(0)
	v_add_f32_e32 v38, v38, v39
	ds_bpermute_b32 v39, v92, v38
	s_waitcnt lgkmcnt(0)
	v_add_f32_e32 v38, v38, v39
	ds_bpermute_b32 v39, v93, v38
	s_waitcnt lgkmcnt(0)
	v_add_f32_e32 v38, v38, v39
	ds_bpermute_b32 v39, v94, v38
	s_waitcnt lgkmcnt(0)
	v_add_f32_e32 v38, v38, v39
	v_fmamk_f32 v38, v38, 0x3a800000, v205
	v_cmp_gt_f32_e32 vcc, s88, v38
	v_mul_f32_e32 v39, 0x4f800000, v38
	s_nop 0
	v_cndmask_b32_e32 v38, v38, v39, vcc
	v_sqrt_f32_e32 v39, v38
	s_nop 0
	v_add_u32_e32 v40, -1, v39
	v_fma_f32 v41, -v40, v39, v38
	v_cmp_ge_f32_e64 s[0:1], 0, v41
	v_add_u32_e32 v41, 1, v39
	s_nop 0
	v_cndmask_b32_e64 v40, v39, v40, s[0:1]
	v_fma_f32 v39, -v41, v39, v38
	v_cmp_lt_f32_e64 s[0:1], 0, v39
	s_nop 1
	v_cndmask_b32_e64 v39, v40, v41, s[0:1]
	v_mul_f32_e32 v40, 0x37800000, v39
	v_cndmask_b32_e32 v39, v39, v40, vcc
	v_cmp_class_f32_e32 vcc, v38, v206
	s_nop 1
	v_cndmask_b32_e32 v38, v39, v38, vcc
	v_div_scale_f32 v39, s[0:1], v38, v38, 1.0
	s_lshr_b32 s0, s20, 11
	s_mulk_i32 s0, 0x1800
	s_ashr_i32 s1, s0, 31
	s_lshl_b64 s[0:1], s[0:1], 2
	s_add_u32 s0, s21, s0
	s_addc_u32 s1, s22, s1
	s_add_u32 s2, s0, 0x1000
	s_addc_u32 s3, s1, 0
	global_load_dwordx4 v[96:99], v[78:79], off
	global_load_dwordx4 v[100:103], v76, s[2:3]
	global_load_dwordx4 v[104:107], v76, s[0:1]
	v_rcp_f32_e32 v40, v39
	s_add_i32 s10, s8, 1
	s_add_i32 s12, s8, 2
	s_add_i32 s16, s8, 3
	v_fma_f32 v41, -v39, v40, 1.0
	v_fmac_f32_e32 v40, v41, v40
	v_div_scale_f32 v41, vcc, 1.0, v38, 1.0
	v_mul_f32_e32 v77, v41, v40
	v_fma_f32 v86, -v39, v77, v41
	v_fmac_f32_e32 v77, v86, v40
	v_fma_f32 v39, -v39, v77, v41
	v_div_fmas_f32 v39, v39, v40, v77
	v_div_fixup_f32 v86, v39, v38, 1.0
	s_ashr_i32 s11, s10, 31
	s_ashr_i32 s13, s12, 31
	v_pk_mul_f32 v[58:59], v[58:59], v[86:87] op_sel_hi:[1,0]
	v_pk_mul_f32 v[60:61], v[60:61], v[86:87] op_sel_hi:[1,0]
	s_ashr_i32 s17, s16, 31
	s_lshl_b64 s[18:19], s[8:9], 11
	s_lshl_b64 s[10:11], s[10:11], 11
	s_lshl_b64 s[12:13], s[12:13], 11
	s_lshl_b64 s[16:17], s[16:17], 11
	v_lshlrev_b32_e32 v38, 1, v85
	v_pk_mul_f32 v[42:43], v[42:43], v[86:87] op_sel_hi:[1,0]
	v_pk_mul_f32 v[44:45], v[44:45], v[86:87] op_sel_hi:[1,0]
	s_waitcnt vmcnt(1)
	v_pk_add_f32 v[102:103], v[102:103], 1.0 op_sel_hi:[1,0]
	v_pk_add_f32 v[100:101], v[100:101], 1.0 op_sel_hi:[1,0]
	v_pk_mul_f32 v[98:99], v[98:99], v[102:103]
	v_pk_mul_f32 v[96:97], v[96:97], v[100:101]
	s_waitcnt vmcnt(0)
	v_pk_fma_f32 v[72:73], v[72:73], v[98:99], v[106:107]
	v_pk_fma_f32 v[70:71], v[70:71], v[96:97], v[104:105]
	v_pk_fma_f32 v[68:69], v[68:69], v[98:99], v[106:107]
	v_pk_fma_f32 v[66:67], v[66:67], v[96:97], v[104:105]
	v_pk_fma_f32 v[64:65], v[64:65], v[98:99], v[106:107]
	v_pk_fma_f32 v[62:63], v[62:63], v[96:97], v[104:105]
	v_pk_fma_f32 v[60:61], v[98:99], v[60:61], v[106:107]
	v_pk_fma_f32 v[58:59], v[96:97], v[58:59], v[104:105]
	v_cvt_pk_bf16_f32 v70, v70, v71
	v_cvt_pk_bf16_f32 v71, v72, v73
	v_lshl_add_u64 v[72:73], v[74:75], 0, s[18:19]
	v_cvt_pk_bf16_f32 v66, v66, v67
	v_cvt_pk_bf16_f32 v67, v68, v69
	v_lshl_add_u64 v[68:69], v[74:75], 0, s[10:11]
	v_cvt_pk_bf16_f32 v62, v62, v63
	v_cvt_pk_bf16_f32 v63, v64, v65
	v_lshl_add_u64 v[64:65], v[74:75], 0, s[12:13]
	v_cvt_pk_bf16_f32 v58, v58, v59
	v_cvt_pk_bf16_f32 v59, v60, v61
	v_lshl_add_u64 v[60:61], v[74:75], 0, s[16:17]
	global_store_dwordx2 v[72:73], v[70:71], off sc1 nt
	global_store_dwordx2 v[68:69], v[66:67], off sc1 nt
	global_store_dwordx2 v[64:65], v[62:63], off sc1 nt
	global_store_dwordx2 v[60:61], v[58:59], off sc1 nt
	v_lshlrev_b32_e32 v62, 2, v85
	global_load_dwordx4 v[58:61], v[78:79], off offset:1024
	s_nop 0
	global_load_dwordx4 v[62:65], v62, s[2:3]
	s_nop 0
	global_load_dwordx4 v[66:69], v76, s[0:1] offset:1024
	s_add_u32 s18, s90, s18
	s_addc_u32 s19, s91, s19
	s_add_u32 s10, s90, s10
	s_addc_u32 s11, s91, s11
	s_add_u32 s12, s90, s12
	s_addc_u32 s13, s91, s13
	s_add_u32 s16, s90, s16
	s_addc_u32 s17, s91, s17
	s_add_i32 s20, s20, s52
	s_add_i32 s8, s8, s59
	s_cmpk_gt_i32 s20, 0x1fff
	s_waitcnt vmcnt(1)
	v_pk_add_f32 v[62:63], v[62:63], 1.0 op_sel_hi:[1,0]
	v_pk_add_f32 v[64:65], v[64:65], 1.0 op_sel_hi:[1,0]
	v_pk_mul_f32 v[58:59], v[58:59], v[62:63]
	v_pk_mul_f32 v[60:61], v[60:61], v[64:65]
	s_waitcnt vmcnt(0)
; __device__ __forceinline__ unsigned pk2(float lo, float hi) { return cvtpk(lo, hi); }
; template <int NR>
; __device__ __forceinline__ void norm_group(int m0, const float* src_lat, const float* src_ctx, bf16* H, const float* gain, const float* mod, int shoff, int scoff, int lane, const float* part, float* ctx_out) {
;     ...
;     const float* mr = mod + b * 6144;
; #pragma unroll
;     for (int j = 0; j < 4; ++j) { const int idx = 4 * (lane + 64 * j);
;         const f32x4 g = *(const f32x4*)(gain + idx), sc = *(const f32x4*)(mr + scoff + idx), sh = *(const f32x4*)(mr + shoff + idx);
;         const f32x4 gs = g * (1.f + sc);
; #pragma unroll
;         for (int i = 0; i < NR; ++i) { const f32x4 y = v[i][j] * rstd[i] * gs + sh;
;             v2u o; o.x = pk2(y.x, y.y); o.y = pk2(y.z, y.w);
;             *(v2u*)(H + (size_t)(m0 + i) * D + idx) = o; } }
	v_pk_fma_f32 v[46:47], v[46:47], v[58:59], v[66:67]
	v_pk_fma_f32 v[48:49], v[48:49], v[60:61], v[68:69]
	v_cvt_pk_bf16_f32 v46, v46, v47
	v_pk_fma_f32 v[54:55], v[54:55], v[58:59], v[66:67]
	v_cvt_pk_bf16_f32 v47, v48, v49
	global_store_dwordx2 v38, v[46:47], s[10:11] sc1 nt
	v_pk_mul_f32 v[46:47], v[50:51], v[84:85] op_sel_hi:[1,0]
	v_pk_mul_f32 v[48:49], v[52:53], v[84:85] op_sel_hi:[1,0]
	v_pk_fma_f32 v[46:47], v[46:47], v[58:59], v[66:67]
	v_pk_fma_f32 v[42:43], v[42:43], v[58:59], v[66:67]
	v_pk_fma_f32 v[56:57], v[56:57], v[60:61], v[68:69]
	v_cvt_pk_bf16_f32 v54, v54, v55
	v_pk_fma_f32 v[48:49], v[48:49], v[60:61], v[68:69]
	v_cvt_pk_bf16_f32 v55, v56, v57
	global_store_dwordx2 v38, v[54:55], s[18:19] sc1 nt
	v_cvt_pk_bf16_f32 v46, v46, v47
	v_cvt_pk_bf16_f32 v47, v48, v49
	global_store_dwordx2 v38, v[46:47], s[12:13] sc1 nt
	v_pk_fma_f32 v[44:45], v[44:45], v[60:61], v[68:69]
	v_cvt_pk_bf16_f32 v42, v42, v43
	s_nop 0
	v_cvt_pk_bf16_f32 v43, v44, v45
	global_store_dwordx2 v38, v[42:43], s[16:17] sc1 nt
	v_lshlrev_b32_e32 v38, 2, v87
	global_load_dwordx4 v[42:45], v[78:79], off offset:2048
	global_load_dwordx4 v[46:49], v38, s[2:3]
	global_load_dwordx4 v[50:53], v76, s[0:1] offset:2048
	s_waitcnt vmcnt(1)
	v_pk_add_f32 v[48:49], v[48:49], 1.0 op_sel_hi:[1,0]
	v_pk_add_f32 v[46:47], v[46:47], 1.0 op_sel_hi:[1,0]
	v_pk_mul_f32 v[44:45], v[44:45], v[48:49]
	v_pk_mul_f32 v[42:43], v[42:43], v[46:47]
	s_waitcnt vmcnt(0)
	v_pk_fma_f32 v[32:33], v[32:33], v[44:45], v[52:53]
	v_pk_fma_f32 v[30:31], v[30:31], v[42:43], v[50:51]
	v_pk_fma_f32 v[18:19], v[18:19], v[42:43], v[50:51]
	v_cvt_pk_bf16_f32 v30, v30, v31
	v_cvt_pk_bf16_f32 v31, v32, v33
	v_lshlrev_b32_e32 v32, 1, v87
	v_pk_fma_f32 v[20:21], v[20:21], v[44:45], v[52:53]
	v_cvt_pk_bf16_f32 v18, v18, v19
	global_store_dwordx2 v32, v[30:31], s[18:19] sc1 nt
	v_cvt_pk_bf16_f32 v19, v20, v21
	global_store_dwordx2 v32, v[18:19], s[10:11] sc1 nt
	v_pk_mul_f32 v[18:19], v[26:27], v[84:85] op_sel_hi:[1,0]
	v_pk_mul_f32 v[20:21], v[28:29], v[84:85] op_sel_hi:[1,0]
	v_pk_fma_f32 v[18:19], v[18:19], v[42:43], v[50:51]
	v_pk_fma_f32 v[20:21], v[20:21], v[44:45], v[52:53]
	v_cvt_pk_bf16_f32 v18, v18, v19
	s_nop 0
	v_cvt_pk_bf16_f32 v19, v20, v21
	global_store_dwordx2 v32, v[18:19], s[12:13] sc1 nt
	v_pk_mul_f32 v[18:19], v[22:23], v[86:87] op_sel_hi:[1,0]
	v_pk_mul_f32 v[20:21], v[24:25], v[86:87] op_sel_hi:[1,0]
	v_pk_fma_f32 v[18:19], v[18:19], v[42:43], v[50:51]
	v_pk_fma_f32 v[20:21], v[20:21], v[44:45], v[52:53]
	v_cvt_pk_bf16_f32 v18, v18, v19
	v_lshlrev_b32_e32 v22, 2, v88
	v_cvt_pk_bf16_f32 v19, v20, v21
	global_store_dwordx2 v32, v[18:19], s[16:17] sc1 nt
	global_load_dwordx4 v[18:21], v[78:79], off offset:3072
	s_nop 0
	global_load_dwordx4 v[22:25], v22, s[2:3]
	s_nop 0
	global_load_dwordx4 v[26:29], v76, s[0:1] offset:3072
	s_waitcnt vmcnt(1)
	v_pk_add_f32 v[24:25], v[24:25], 1.0 op_sel_hi:[1,0]
	v_pk_add_f32 v[22:23], v[22:23], 1.0 op_sel_hi:[1,0]
	v_pk_mul_f32 v[20:21], v[20:21], v[24:25]
	v_pk_mul_f32 v[18:19], v[18:19], v[22:23]
	s_waitcnt vmcnt(0)
	v_pk_fma_f32 v[16:17], v[16:17], v[20:21], v[28:29]
	v_pk_fma_f32 v[14:15], v[14:15], v[18:19], v[26:27]
	v_pk_fma_f32 v[2:3], v[2:3], v[18:19], v[26:27]
	v_cvt_pk_bf16_f32 v14, v14, v15
	v_cvt_pk_bf16_f32 v15, v16, v17
	v_lshlrev_b32_e32 v16, 1, v88
	v_pk_fma_f32 v[4:5], v[4:5], v[20:21], v[28:29]
	v_cvt_pk_bf16_f32 v2, v2, v3
	global_store_dwordx2 v16, v[14:15], s[18:19] sc1 nt
	v_cvt_pk_bf16_f32 v3, v4, v5
	global_store_dwordx2 v16, v[2:3], s[10:11] sc1 nt
	v_pk_mul_f32 v[2:3], v[10:11], v[84:85] op_sel_hi:[1,0]
	v_pk_mul_f32 v[4:5], v[12:13], v[84:85] op_sel_hi:[1,0]
	v_pk_fma_f32 v[2:3], v[2:3], v[18:19], v[26:27]
	v_pk_fma_f32 v[4:5], v[4:5], v[20:21], v[28:29]
	v_cvt_pk_bf16_f32 v2, v2, v3
	s_nop 0
	v_cvt_pk_bf16_f32 v3, v4, v5
	global_store_dwordx2 v16, v[2:3], s[12:13] sc1 nt
	v_pk_mul_f32 v[2:3], v[6:7], v[86:87] op_sel_hi:[1,0]
	v_pk_mul_f32 v[4:5], v[8:9], v[86:87] op_sel_hi:[1,0]
	v_pk_fma_f32 v[2:3], v[2:3], v[18:19], v[26:27]
	v_pk_fma_f32 v[4:5], v[4:5], v[20:21], v[28:29]
	v_cvt_pk_bf16_f32 v2, v2, v3
	s_nop 0
	v_cvt_pk_bf16_f32 v3, v4, v5
	global_store_dwordx2 v16, v[2:3], s[16:17] sc1 nt
	s_cbranch_scc0 .LBB0_110

; template <int NR>
; __device__ __forceinline__ void norm_group(int m0, const float* src_lat, const float* src_ctx, bf16* H, const float* gain, const float* mod, int shoff, int scoff, int lane, const float* part, float* ctx_out) {
;     const float* xr = (m0 < MLAT) ? src_lat + (size_t)m0 * D : src_ctx + (size_t)(m0 - MLAT) * D;
;     const int b = (m0 < MLAT) ? (m0 >> 13) : 4;
;     f32x4 v[NR][4]; float rstd[NR];
; #pragma unroll
;     for (int i = 0; i < NR; ++i)
; #pragma unroll
;         for (int j = 0; j < 4; ++j) v[i][j] = *((const f32x4*)(xr + (size_t)i * D) + lane + 64 * j);
;     if (part && m0 >= MLAT) {
; #pragma unroll
;         for (int i = 0; i < NR; ++i)
; #pragma unroll
;             for (int j = 0; j < 4; ++j) { const size_t o = (size_t)(m0 - MLAT + i) * D + 4 * (lane + 64 * j);
;                 const f32x4 p0 = *(const f32x4*)(part + o), p1 = *(const f32x4*)(part + (size_t)MCTX * D + o), p2 = *(const f32x4*)(part + (size_t)2 * MCTX * D + o), p3 = *(const f32x4*)(part + (size_t)3 * MCTX * D + o);
;                 v[i][j] = v[i][j] + ((p0 + p1) + (p2 + p3)); *(f32x4*)(ctx_out + o) = v[i][j]; }
;     }
; #pragma unroll
;     for (int i = 0; i < NR; ++i) { float s = 0.f;
; #pragma unroll
;         for (int j = 0; j < 4; ++j) s += (v[i][j].x * v[i][j].x + v[i][j].y * v[i][j].y) + (v[i][j].z * v[i][j].z + v[i][j].w * v[i][j].w);
;         rstd[i] = 1.0f / sqrtf(wave_sum(s) * (1.f / D) + EPS); }
;     const float* mr = mod + b * 6144;
; #pragma unroll
;     for (int j = 0; j < 4; ++j) { const int idx = 4 * (lane + 64 * j);
;         const f32x4 g = *(const f32x4*)(gain + idx), sc = *(const f32x4*)(mr + scoff + idx), sh = *(const f32x4*)(mr + shoff + idx);
;         const f32x4 gs = g * (1.f + sc);
; #pragma unroll
;         for (int i = 0; i < NR; ++i) { const f32x4 y = v[i][j] * rstd[i] * gs + sh;
;             v2u o; o.x = pk2(y.x, y.y); o.y = pk2(y.z, y.w);
;             *(v2u*)(H + (size_t)(m0 + i) * D + idx) = o; } }
; __device__ __forceinline__ void norm_pass(const float* src_lat, const float* src_ctx, bf16* H, const float* gain, const float* mod, int shoff, int scoff, int nrows, int lane, int wave, const float* part = nullptr, float* ctx_out = nullptr) {
;     ...
;     for (int m = MLAT + gw; m < nrows; m += NGW) norm_group<1>(m, src_lat, src_ctx, H, gain, mod, shoff, scoff, lane, part, ctx_out);
.LBB0_113:
	s_min_i32 s0, s6, 0x8000
	s_ashr_i32 s0, s0, 13
	s_waitcnt vmcnt(3)
	v_pk_mul_f32 v[36:37], v[16:17], v[16:17]
	v_pk_mul_f32 v[42:43], v[14:15], v[14:15]
	s_mulk_i32 s0, 0x1800
	s_waitcnt vmcnt(2)
	v_pk_mul_f32 v[30:31], v[12:13], v[12:13]
	v_pk_mul_f32 v[32:33], v[10:11], v[10:11]
	v_pk_mov_b32 v[44:45], v[42:43], v[36:37] op_sel:[1,0]
	v_mov_b32_e32 v43, v37
	s_ashr_i32 s1, s0, 31
	v_pk_add_f32 v[36:37], v[44:45], v[42:43]
	v_pk_mov_b32 v[42:43], v[32:33], v[30:31] op_sel:[1,0]
	v_mov_b32_e32 v33, v31
	s_lshl_b64 s[0:1], s[0:1], 2
	v_readlane_b32 s6, v255, 4
	v_pk_add_f32 v[30:31], v[42:43], v[32:33]
	s_add_u32 s6, s6, s0
	v_readlane_b32 s0, v255, 3
	v_pk_add_f32 v[46:47], v[30:31], v[30:31] op_sel_hi:[0,1]
	s_waitcnt vmcnt(1)
	v_mul_f32_e32 v30, v6, v6
	s_addc_u32 s7, s0, s1
	v_pk_fma_f32 v[42:43], v[6:7], v[6:7], v[30:31] op_sel_hi:[1,1,0]
	v_mul_f32_e32 v30, v8, v8
	s_add_u32 s18, s6, 0x1000
	v_pk_fma_f32 v[44:45], v[8:9], v[8:9], v[30:31] op_sel_hi:[1,1,0]
	s_addc_u32 s19, s7, 0
	v_pk_add_f32 v[36:37], v[36:37], v[36:37] op_sel_hi:[0,1]
	s_waitcnt vmcnt(0)
	v_mul_f32_e32 v42, v2, v2
	v_mul_f32_e32 v44, v3, v3
	global_load_dwordx4 v[30:33], v18, s[18:19]
	v_mul_f32_e32 v36, v4, v4
	v_mul_f32_e32 v46, v5, v5
	v_pk_add_f32 v[50:51], v[42:43], v[44:45]
	global_load_dwordx4 v[42:45], v[20:21], off
	v_pk_add_f32 v[36:37], v[36:37], v[46:47]
	global_load_dwordx4 v[46:49], v18, s[6:7]
	v_pk_add_f32 v[36:37], v[50:51], v[36:37]
	s_add_i32 s78, s78, s52
	v_add_f32_e32 v19, v36, v37
	ds_bpermute_b32 v36, v24, v19
	s_waitcnt lgkmcnt(0)
	v_add_f32_e32 v19, v19, v36
	ds_bpermute_b32 v36, v25, v19
	s_waitcnt lgkmcnt(0)
	v_add_f32_e32 v19, v19, v36
	ds_bpermute_b32 v36, v26, v19
	s_waitcnt lgkmcnt(0)
	v_add_f32_e32 v19, v19, v36
	ds_bpermute_b32 v36, v27, v19
	s_waitcnt lgkmcnt(0)
	v_add_f32_e32 v19, v19, v36
	ds_bpermute_b32 v36, v28, v19
	s_waitcnt lgkmcnt(0)
	v_add_f32_e32 v19, v19, v36
	ds_bpermute_b32 v36, v29, v19
	s_waitcnt lgkmcnt(0)
	v_add_f32_e32 v19, v19, v36
	v_fmamk_f32 v19, v19, 0x3a800000, v205
	v_mul_f32_e32 v36, 0x4f800000, v19
	v_cmp_gt_f32_e32 vcc, s88, v19
	s_waitcnt vmcnt(2)
	v_pk_add_f32 v[30:31], v[30:31], 1.0 op_sel_hi:[1,0]
	v_cndmask_b32_e32 v19, v19, v36, vcc
	v_sqrt_f32_e32 v36, v19
	v_pk_add_f32 v[32:33], v[32:33], 1.0 op_sel_hi:[1,0]
	s_waitcnt vmcnt(1)
	v_pk_mul_f32 v[30:31], v[42:43], v[30:31]
	v_pk_mul_f32 v[32:33], v[44:45], v[32:33]
	v_add_u32_e32 v37, -1, v36
	v_add_u32_e32 v38, 1, v36
	v_fma_f32 v39, -v37, v36, v19
	v_fma_f32 v40, -v38, v36, v19
	v_cmp_ge_f32_e64 s[0:1], 0, v39
	s_nop 1
	v_cndmask_b32_e64 v36, v36, v37, s[0:1]
	v_cmp_lt_f32_e64 s[0:1], 0, v40
	s_nop 1
	v_cndmask_b32_e64 v36, v36, v38, s[0:1]
	v_mul_f32_e32 v37, 0x37800000, v36
	v_cndmask_b32_e32 v36, v36, v37, vcc
	v_cmp_class_f32_e32 vcc, v19, v206
	v_lshlrev_b32_e32 v38, 2, v85
	s_nop 0
	v_cndmask_b32_e32 v19, v36, v19, vcc
	v_div_scale_f32 v36, s[0:1], v19, v19, 1.0
	v_rcp_f32_e32 v37, v36
	v_div_scale_f32 v39, vcc, 1.0, v19, 1.0
	s_add_i32 s0, s78, 0x8000
	v_fma_f32 v40, -v36, v37, 1.0
	v_fmac_f32_e32 v37, v40, v37
	v_mul_f32_e32 v40, v39, v37
	v_fma_f32 v41, -v36, v40, v39
	v_fmac_f32_e32 v40, v41, v37
	v_fma_f32 v36, -v36, v40, v39
	v_div_fmas_f32 v36, v36, v37, v40
	v_div_fixup_f32 v36, v36, v19, 1.0
	v_pk_mul_f32 v[14:15], v[14:15], v[36:37] op_sel_hi:[1,0]
	v_pk_mul_f32 v[16:17], v[16:17], v[36:37] op_sel_hi:[1,0]
	s_waitcnt vmcnt(0)
	v_pk_fma_f32 v[14:15], v[30:31], v[14:15], v[46:47]
	v_pk_fma_f32 v[16:17], v[32:33], v[16:17], v[48:49]
	v_cvt_pk_bf16_f32 v14, v14, v15
	v_pk_mul_f32 v[10:11], v[10:11], v[36:37] op_sel_hi:[1,0]
	v_cvt_pk_bf16_f32 v15, v16, v17
	global_store_dwordx2 v[22:23], v[14:15], off sc1 nt
	global_load_dwordx4 v[14:17], v38, s[18:19]
	s_nop 0
	global_load_dwordx4 v[30:33], v[20:21], off offset:1024
	global_load_dwordx4 v[42:45], v18, s[6:7] offset:1024
	v_pk_mul_f32 v[12:13], v[12:13], v[36:37] op_sel_hi:[1,0]
	v_lshlrev_b32_e32 v19, 2, v87
	v_pk_mul_f32 v[6:7], v[6:7], v[36:37] op_sel_hi:[1,0]
	v_pk_mul_f32 v[8:9], v[8:9], v[36:37] op_sel_hi:[1,0]
	s_add_u32 s2, s2, s52
	v_pk_mul_f32 v[2:3], v[2:3], v[36:37] op_sel_hi:[1,0]
	s_addc_u32 s3, s3, s53
	v_pk_mul_f32 v[4:5], v[4:5], v[36:37] op_sel_hi:[1,0]
	s_cmp_lt_i32 s0, 0x8400
	s_waitcnt vmcnt(2)
	v_pk_add_f32 v[14:15], v[14:15], 1.0 op_sel_hi:[1,0]
	v_pk_add_f32 v[16:17], v[16:17], 1.0 op_sel_hi:[1,0]
	s_waitcnt vmcnt(1)
	v_pk_mul_f32 v[14:15], v[30:31], v[14:15]
	v_pk_mul_f32 v[16:17], v[32:33], v[16:17]
	s_waitcnt vmcnt(0)
	v_pk_fma_f32 v[10:11], v[14:15], v[10:11], v[42:43]
	v_pk_fma_f32 v[12:13], v[16:17], v[12:13], v[44:45]
	v_cvt_pk_bf16_f32 v10, v10, v11
	s_nop 0
	v_cvt_pk_bf16_f32 v11, v12, v13
	global_store_dwordx2 v[22:23], v[10:11], off offset:512 sc1 nt
	global_load_dwordx4 v[10:13], v19, s[18:19]
	s_nop 0
	global_load_dwordx4 v[14:17], v[20:21], off offset:2048
	global_load_dwordx4 v[30:33], v18, s[6:7] offset:2048
	v_lshlrev_b32_e32 v19, 2, v88
	s_waitcnt vmcnt(2)
	v_pk_add_f32 v[10:11], v[10:11], 1.0 op_sel_hi:[1,0]
	v_pk_add_f32 v[12:13], v[12:13], 1.0 op_sel_hi:[1,0]
	s_waitcnt vmcnt(1)
	v_pk_mul_f32 v[10:11], v[14:15], v[10:11]
	v_pk_mul_f32 v[12:13], v[16:17], v[12:13]
	s_waitcnt vmcnt(0)
	v_pk_fma_f32 v[6:7], v[6:7], v[10:11], v[30:31]
	v_pk_fma_f32 v[8:9], v[8:9], v[12:13], v[32:33]
	v_cvt_pk_bf16_f32 v6, v6, v7
	s_nop 0
	v_cvt_pk_bf16_f32 v7, v8, v9
	global_store_dwordx2 v[22:23], v[6:7], off offset:1024 sc1 nt
	global_load_dwordx4 v[6:9], v19, s[18:19]
	s_nop 0
	global_load_dwordx4 v[10:13], v[20:21], off offset:3072
	global_load_dwordx4 v[14:17], v18, s[6:7] offset:3072
	s_waitcnt vmcnt(2)
	v_pk_add_f32 v[6:7], v[6:7], 1.0 op_sel_hi:[1,0]
	v_pk_add_f32 v[8:9], v[8:9], 1.0 op_sel_hi:[1,0]
	s_waitcnt vmcnt(1)
	v_pk_mul_f32 v[6:7], v[10:11], v[6:7]
	v_pk_mul_f32 v[8:9], v[12:13], v[8:9]
	s_waitcnt vmcnt(0)
	v_pk_fma_f32 v[2:3], v[2:3], v[6:7], v[14:15]
	v_pk_fma_f32 v[4:5], v[4:5], v[8:9], v[16:17]
	v_cvt_pk_bf16_f32 v2, v2, v3
	s_nop 0
	v_cvt_pk_bf16_f32 v3, v4, v5
	global_store_dwordx2 v[22:23], v[2:3], off offset:1536 sc1 nt
	v_lshl_add_u64 v[22:23], v[22:23], 0, s[66:67]
	s_cbranch_scc0 .LBB0_118

; template <int NR>
; __device__ __forceinline__ void norm_group(int m0, const float* src_lat, const float* src_ctx, bf16* H, const float* gain, const float* mod, int shoff, int scoff, int lane, const float* part, float* ctx_out) {
;     ...
;     if (part && m0 >= MLAT) {
; #pragma unroll
;         for (int i = 0; i < NR; ++i)
; #pragma unroll
;             for (int j = 0; j < 4; ++j) { const size_t o = (size_t)(m0 - MLAT + i) * D + 4 * (lane + 64 * j);
;                 const f32x4 p0 = *(const f32x4*)(part + o), p1 = *(const f32x4*)(part + (size_t)MCTX * D + o), p2 = *(const f32x4*)(part + (size_t)2 * MCTX * D + o), p3 = *(const f32x4*)(part + (size_t)3 * MCTX * D + o);
;                 v[i][j] = v[i][j] + ((p0 + p1) + (p2 + p3)); *(f32x4*)(ctx_out + o) = v[i][j]; }
.LBB0_116:
	s_andn2_b64 vcc, exec, s[0:1]
	s_cbranch_vccnz .LBB0_113
	s_lshl_b64 s[0:1], s[78:79], 10
	v_mov_b32_e32 v31, s1
	v_or_b32_e32 v30, s0, v83
	v_lshlrev_b64 v[36:37], 2, v[30:31]
	v_lshl_add_u64 v[54:55], s[4:5], 0, v[36:37]
	v_lshl_add_u64 v[42:43], s[10:11], 0, v[36:37]
	v_lshl_add_u64 v[46:47], s[12:13], 0, v[36:37]
	v_lshl_add_u64 v[50:51], s[16:17], 0, v[36:37]
	global_load_dwordx4 v[30:33], v[54:55], off
	s_nop 0
	global_load_dwordx4 v[42:45], v[42:43], off
	s_nop 0
	global_load_dwordx4 v[46:49], v[46:47], off
	s_nop 0
	global_load_dwordx4 v[50:53], v[50:51], off
	v_mov_b32_e32 v57, s1
	v_or_b32_e32 v56, s0, v85
	v_lshl_add_u64 v[36:37], s[94:95], 0, v[36:37]
	v_lshlrev_b64 v[56:57], 2, v[56:57]
	v_lshl_add_u64 v[58:59], s[10:11], 0, v[56:57]
	v_lshl_add_u64 v[60:61], s[12:13], 0, v[56:57]
	v_lshl_add_u64 v[62:63], s[16:17], 0, v[56:57]
	v_lshl_add_u64 v[56:57], s[94:95], 0, v[56:57]
	s_waitcnt vmcnt(2)
	v_pk_add_f32 v[32:33], v[32:33], v[44:45]
	v_pk_add_f32 v[30:31], v[30:31], v[42:43]
	s_waitcnt vmcnt(0)
	v_pk_add_f32 v[42:43], v[48:49], v[52:53]
	v_pk_add_f32 v[44:45], v[46:47], v[50:51]
	v_pk_add_f32 v[32:33], v[32:33], v[42:43]
	v_pk_add_f32 v[30:31], v[30:31], v[44:45]
	v_pk_add_f32 v[16:17], v[16:17], v[32:33]
	v_pk_add_f32 v[14:15], v[14:15], v[30:31]
	global_store_dwordx4 v[36:37], v[14:17], off sc1 nt
	global_load_dwordx4 v[30:33], v[54:55], off offset:1024
	global_load_dwordx4 v[42:45], v[58:59], off
	global_load_dwordx4 v[46:49], v[60:61], off
	global_load_dwordx4 v[50:53], v[62:63], off
	v_mov_b32_e32 v37, s1
	v_or_b32_e32 v36, s0, v87
	v_lshlrev_b64 v[36:37], 2, v[36:37]
	v_lshl_add_u64 v[58:59], s[10:11], 0, v[36:37]
	v_lshl_add_u64 v[60:61], s[12:13], 0, v[36:37]
	v_lshl_add_u64 v[62:63], s[16:17], 0, v[36:37]
	v_lshl_add_u64 v[36:37], s[94:95], 0, v[36:37]
	s_waitcnt vmcnt(2)
	v_pk_add_f32 v[32:33], v[32:33], v[44:45]
	v_pk_add_f32 v[30:31], v[30:31], v[42:43]
	s_waitcnt vmcnt(0)
	v_pk_add_f32 v[42:43], v[48:49], v[52:53]
	v_pk_add_f32 v[44:45], v[46:47], v[50:51]
	v_pk_add_f32 v[32:33], v[32:33], v[42:43]
	v_pk_add_f32 v[30:31], v[30:31], v[44:45]
	v_pk_add_f32 v[12:13], v[12:13], v[32:33]
	v_pk_add_f32 v[10:11], v[10:11], v[30:31]
	global_store_dwordx4 v[56:57], v[10:13], off sc1 nt
	global_load_dwordx4 v[30:33], v[54:55], off offset:2048
	global_load_dwordx4 v[42:45], v[58:59], off
	global_load_dwordx4 v[46:49], v[60:61], off
	global_load_dwordx4 v[50:53], v[62:63], off
	v_mov_b32_e32 v57, s1
	v_or_b32_e32 v56, s0, v88
	v_lshlrev_b64 v[56:57], 2, v[56:57]
	v_lshl_add_u64 v[58:59], s[10:11], 0, v[56:57]
	v_lshl_add_u64 v[60:61], s[12:13], 0, v[56:57]
	v_lshl_add_u64 v[62:63], s[16:17], 0, v[56:57]
	s_waitcnt vmcnt(2)
	v_pk_add_f32 v[32:33], v[32:33], v[44:45]
	v_pk_add_f32 v[30:31], v[30:31], v[42:43]
	s_waitcnt vmcnt(0)
	v_pk_add_f32 v[42:43], v[48:49], v[52:53]
	v_pk_add_f32 v[44:45], v[46:47], v[50:51]
	v_pk_add_f32 v[32:33], v[32:33], v[42:43]
	v_pk_add_f32 v[30:31], v[30:31], v[44:45]
	v_pk_add_f32 v[8:9], v[8:9], v[32:33]
	v_pk_add_f32 v[6:7], v[6:7], v[30:31]
	global_store_dwordx4 v[36:37], v[6:9], off sc1 nt
	global_load_dwordx4 v[30:33], v[54:55], off offset:3072
	global_load_dwordx4 v[42:45], v[58:59], off
	global_load_dwordx4 v[46:49], v[60:61], off
	global_load_dwordx4 v[50:53], v[62:63], off
	s_waitcnt vmcnt(2)
	v_pk_add_f32 v[32:33], v[32:33], v[44:45]
	v_pk_add_f32 v[30:31], v[30:31], v[42:43]
	s_waitcnt vmcnt(0)
	v_pk_add_f32 v[36:37], v[48:49], v[52:53]
	v_pk_add_f32 v[42:43], v[46:47], v[50:51]
	v_pk_add_f32 v[32:33], v[32:33], v[36:37]
	v_pk_add_f32 v[30:31], v[30:31], v[42:43]
	v_pk_add_f32 v[4:5], v[4:5], v[32:33]
	v_pk_add_f32 v[2:3], v[2:3], v[30:31]
	v_lshl_add_u64 v[30:31], s[94:95], 0, v[56:57]
	global_store_dwordx4 v[30:31], v[2:5], off sc1 nt
	s_branch .LBB0_113

; template <int NR>
; __device__ __forceinline__ void norm_group(int m0, const float* src_lat, const float* src_ctx, bf16* H, const float* gain, const float* mod, int shoff, int scoff, int lane, const float* part, float* ctx_out) {
;     const float* xr = (m0 < MLAT) ? src_lat + (size_t)m0 * D : src_ctx + (size_t)(m0 - MLAT) * D;
;     const int b = (m0 < MLAT) ? (m0 >> 13) : 4;
;     f32x4 v[NR][4]; float rstd[NR];
; #pragma unroll
;     for (int i = 0; i < NR; ++i)
; #pragma unroll
;         for (int j = 0; j < 4; ++j) v[i][j] = *((const f32x4*)(xr + (size_t)i * D) + lane + 64 * j);
;     if (part && m0 >= MLAT) {
; #pragma unroll
;         for (int i = 0; i < NR; ++i)
; #pragma unroll
;             for (int j = 0; j < 4; ++j) { const size_t o = (size_t)(m0 - MLAT + i) * D + 4 * (lane + 64 * j);
;                 const f32x4 p0 = *(const f32x4*)(part + o), p1 = *(const f32x4*)(part + (size_t)MCTX * D + o), p2 = *(const f32x4*)(part + (size_t)2 * MCTX * D + o), p3 = *(const f32x4*)(part + (size_t)3 * MCTX * D + o);
;                 v[i][j] = v[i][j] + ((p0 + p1) + (p2 + p3)); *(f32x4*)(ctx_out + o) = v[i][j]; }
;     }
; #pragma unroll
;     for (int i = 0; i < NR; ++i) { float s = 0.f;
; #pragma unroll
;         for (int j = 0; j < 4; ++j) s += (v[i][j].x * v[i][j].x + v[i][j].y * v[i][j].y) + (v[i][j].z * v[i][j].z + v[i][j].w * v[i][j].w);
;         rstd[i] = 1.0f / sqrtf(wave_sum(s) * (1.f / D) + EPS); }
.LBB0_615:
	s_ashr_i32 s9, s8, 31
	s_lshl_b64 s[0:1], s[8:9], 12
	v_lshl_add_u64 v[6:7], v[76:77], 0, s[0:1]
	global_load_dwordx4 v[70:73], v[6:7], off
	global_load_dwordx4 v[54:57], v[6:7], off offset:1024
	global_load_dwordx4 v[30:33], v[6:7], off offset:2048
	global_load_dwordx4 v[14:17], v[6:7], off offset:3072
	v_add_co_u32_e32 v2, vcc, 0x1000, v6
	s_waitcnt vmcnt(3)
	v_pk_mul_f32 v[94:95], v[72:73], v[72:73]
	v_addc_co_u32_e32 v3, vcc, 0, v7, vcc
	global_load_dwordx4 v[66:69], v[2:3], off
	global_load_dwordx4 v[46:49], v[2:3], off offset:1024
	global_load_dwordx4 v[18:21], v[2:3], off offset:2048
	s_nop 0
	global_load_dwordx4 v[2:5], v[2:3], off offset:3072
	v_pk_mul_f32 v[96:97], v[70:71], v[70:71]
	s_waitcnt vmcnt(4)
	v_mul_f32_e32 v38, v14, v14
	v_pk_mov_b32 v[98:99], v[96:97], v[94:95] op_sel:[1,0]
	v_mov_b32_e32 v97, v95
	v_pk_add_f32 v[94:95], v[98:99], v[96:97]
	v_pk_mul_f32 v[96:97], v[56:57], v[56:57]
	v_pk_mul_f32 v[98:99], v[54:55], v[54:55]
	v_mul_f32_e32 v39, v15, v15
	v_pk_mov_b32 v[100:101], v[98:99], v[96:97] op_sel:[1,0]
	v_mov_b32_e32 v99, v97
	v_pk_add_f32 v[96:97], v[100:101], v[98:99]
	v_pk_add_f32 v[94:95], v[94:95], v[94:95] op_sel:[0,1] op_sel_hi:[1,0]
	v_pk_add_f32 v[96:97], v[96:97], v[96:97] op_sel:[0,1] op_sel_hi:[1,0]
	v_mov_b32_e32 v95, v38
	v_mov_b32_e32 v97, v39
	v_mul_f32_e32 v80, v31, v31
	v_pk_add_f32 v[94:95], v[94:95], v[96:97]
	v_pk_fma_f32 v[96:97], v[30:31], v[30:31], v[80:81] op_sel_hi:[1,1,0]
	v_mul_f32_e32 v80, v33, v33
	v_mul_f32_e32 v40, v16, v16
	v_mul_f32_e32 v41, v17, v17
	v_pk_fma_f32 v[98:99], v[32:33], v[32:33], v[80:81] op_sel_hi:[1,1,0]
	v_mov_b32_e32 v97, v40
	v_mov_b32_e32 v99, v41
	v_pk_add_f32 v[96:97], v[96:97], v[98:99]
	v_add_co_u32_e32 v8, vcc, s96, v6
	v_pk_add_f32 v[94:95], v[94:95], v[96:97]
	s_nop 0
	v_addc_co_u32_e32 v9, vcc, 0, v7, vcc
	v_add_f32_e32 v38, v94, v95
	ds_bpermute_b32 v39, v37, v38
	v_add_co_u32_e32 v6, vcc, s87, v6
	s_waitcnt lgkmcnt(0)
	v_add_f32_e32 v38, v38, v39
	ds_bpermute_b32 v39, v89, v38
	v_addc_co_u32_e32 v7, vcc, 0, v7, vcc
	global_load_dwordx4 v[62:65], v[6:7], off offset:-4096
	global_load_dwordx4 v[50:53], v[8:9], off offset:1024
	global_load_dwordx4 v[26:29], v[8:9], off offset:2048
	global_load_dwordx4 v[10:13], v[8:9], off offset:3072
	global_load_dwordx4 v[58:61], v[6:7], off
	global_load_dwordx4 v[42:45], v[6:7], off offset:1024
	global_load_dwordx4 v[22:25], v[6:7], off offset:2048
	s_nop 0
	global_load_dwordx4 v[6:9], v[6:7], off offset:3072
	s_waitcnt lgkmcnt(0)
	v_add_f32_e32 v38, v38, v39
	ds_bpermute_b32 v39, v90, v38
	s_waitcnt lgkmcnt(0)
	v_add_f32_e32 v38, v38, v39
	ds_bpermute_b32 v39, v91, v38
	s_waitcnt lgkmcnt(0)
	v_add_f32_e32 v38, v38, v39
	ds_bpermute_b32 v39, v92, v38
	s_waitcnt lgkmcnt(0)
	v_add_f32_e32 v38, v38, v39
	ds_bpermute_b32 v39, v93, v38
	s_waitcnt lgkmcnt(0)
	v_add_f32_e32 v38, v38, v39
	v_fmamk_f32 v38, v38, 0x3a800000, v205
	v_cmp_gt_f32_e32 vcc, s88, v38
	v_mul_f32_e32 v39, 0x4f800000, v38
	s_waitcnt vmcnt(11)
	v_pk_mul_f32 v[94:95], v[68:69], v[68:69]
	v_cndmask_b32_e32 v38, v38, v39, vcc
	v_sqrt_f32_e32 v39, v38
	v_pk_mul_f32 v[96:97], v[66:67], v[66:67]
	v_add_u32_e32 v40, -1, v39
	v_fma_f32 v41, -v40, v39, v38
	v_cmp_ge_f32_e64 s[0:1], 0, v41
	v_add_u32_e32 v41, 1, v39
	v_pk_mov_b32 v[98:99], v[96:97], v[94:95] op_sel:[1,0]
	v_cndmask_b32_e64 v40, v39, v40, s[0:1]
	v_fma_f32 v39, -v41, v39, v38
	v_cmp_lt_f32_e64 s[0:1], 0, v39
	v_mov_b32_e32 v97, v95
	v_pk_add_f32 v[94:95], v[98:99], v[96:97]
	v_cndmask_b32_e64 v39, v40, v41, s[0:1]
	v_mul_f32_e32 v40, 0x37800000, v39
	v_cndmask_b32_e32 v39, v39, v40, vcc
	v_cmp_class_f32_e32 vcc, v38, v206
	s_waitcnt vmcnt(10)
	v_pk_mul_f32 v[96:97], v[48:49], v[48:49]
	v_pk_mul_f32 v[98:99], v[46:47], v[46:47]
	v_cndmask_b32_e32 v38, v39, v38, vcc
	v_div_scale_f32 v39, s[0:1], v38, v38, 1.0
	v_rcp_f32_e32 v40, v39
	v_pk_mov_b32 v[100:101], v[98:99], v[96:97] op_sel:[1,0]
	v_mov_b32_e32 v99, v97
	v_pk_add_f32 v[96:97], v[100:101], v[98:99]
	v_fma_f32 v41, -v39, v40, 1.0
	v_fmac_f32_e32 v40, v41, v40
	v_div_scale_f32 v41, vcc, 1.0, v38, 1.0
	v_mul_f32_e32 v80, v41, v40
	v_fma_f32 v82, -v39, v80, v41
	v_fmac_f32_e32 v80, v82, v40
	v_fma_f32 v39, -v39, v80, v41
	v_div_fmas_f32 v39, v39, v40, v80
	v_div_fixup_f32 v80, v39, v38, 1.0
	s_waitcnt vmcnt(8)
	v_mul_f32_e32 v38, v2, v2
	v_mul_f32_e32 v39, v3, v3
	v_pk_add_f32 v[94:95], v[94:95], v[94:95] op_sel:[0,1] op_sel_hi:[1,0]
	v_pk_add_f32 v[96:97], v[96:97], v[96:97] op_sel:[0,1] op_sel_hi:[1,0]
	v_mov_b32_e32 v95, v38
	v_mov_b32_e32 v97, v39
	v_mul_f32_e32 v82, v19, v19
	v_pk_add_f32 v[94:95], v[94:95], v[96:97]
	v_pk_fma_f32 v[96:97], v[18:19], v[18:19], v[82:83] op_sel_hi:[1,1,0]
	v_mul_f32_e32 v82, v21, v21
	v_mul_f32_e32 v40, v4, v4
	v_mul_f32_e32 v41, v5, v5
	v_pk_fma_f32 v[98:99], v[20:21], v[20:21], v[82:83] op_sel_hi:[1,1,0]
	v_mov_b32_e32 v97, v40
	v_mov_b32_e32 v99, v41
	v_pk_add_f32 v[96:97], v[96:97], v[98:99]
	v_pk_mul_f32 v[70:71], v[70:71], v[80:81] op_sel_hi:[1,0]
	v_pk_add_f32 v[94:95], v[94:95], v[96:97]
	s_waitcnt vmcnt(7)
	v_pk_mul_f32 v[96:97], v[62:63], v[62:63]
	v_add_f32_e32 v38, v94, v95
	ds_bpermute_b32 v39, v37, v38
	v_pk_mul_f32 v[94:95], v[64:65], v[64:65]
	v_pk_mul_f32 v[72:73], v[72:73], v[80:81] op_sel_hi:[1,0]
	v_pk_mov_b32 v[98:99], v[96:97], v[94:95] op_sel:[1,0]
	v_mov_b32_e32 v97, v95
	s_waitcnt lgkmcnt(0)
	v_add_f32_e32 v38, v38, v39
	ds_bpermute_b32 v39, v89, v38
	v_pk_add_f32 v[94:95], v[98:99], v[96:97]
	s_waitcnt vmcnt(6)
	v_pk_mul_f32 v[96:97], v[52:53], v[52:53]
	v_pk_mul_f32 v[98:99], v[50:51], v[50:51]
	v_pk_add_f32 v[94:95], v[94:95], v[94:95] op_sel:[0,1] op_sel_hi:[1,0]
	s_waitcnt lgkmcnt(0)
; template <int NR>
; __device__ __forceinline__ void norm_group(int m0, const float* src_lat, const float* src_ctx, bf16* H, const float* gain, const float* mod, int shoff, int scoff, int lane, const float* part, float* ctx_out) {
;     ...
;     for (int i = 0; i < NR; ++i) { float s = 0.f;
; #pragma unroll
;         for (int j = 0; j < 4; ++j) s += (v[i][j].x * v[i][j].x + v[i][j].y * v[i][j].y) + (v[i][j].z * v[i][j].z + v[i][j].w * v[i][j].w);
;         rstd[i] = 1.0f / sqrtf(wave_sum(s) * (1.f / D) + EPS); }
	v_add_f32_e32 v38, v38, v39
	ds_bpermute_b32 v39, v90, v38
	v_pk_mov_b32 v[100:101], v[98:99], v[96:97] op_sel:[1,0]
	v_mov_b32_e32 v99, v97
	v_pk_add_f32 v[96:97], v[100:101], v[98:99]
	v_pk_mul_f32 v[54:55], v[54:55], v[80:81] op_sel_hi:[1,0]
	s_waitcnt lgkmcnt(0)
	v_add_f32_e32 v38, v38, v39
	ds_bpermute_b32 v39, v91, v38
	v_pk_add_f32 v[96:97], v[96:97], v[96:97] op_sel:[0,1] op_sel_hi:[1,0]
	v_pk_mul_f32 v[56:57], v[56:57], v[80:81] op_sel_hi:[1,0]
	v_pk_mul_f32 v[30:31], v[30:31], v[80:81] op_sel_hi:[1,0]
	v_pk_mul_f32 v[32:33], v[32:33], v[80:81] op_sel_hi:[1,0]
	s_waitcnt lgkmcnt(0)
	v_add_f32_e32 v38, v38, v39
	ds_bpermute_b32 v39, v92, v38
	v_pk_mul_f32 v[14:15], v[14:15], v[80:81] op_sel_hi:[1,0]
	v_pk_mul_f32 v[16:17], v[16:17], v[80:81] op_sel_hi:[1,0]
	s_waitcnt lgkmcnt(0)
	v_add_f32_e32 v38, v38, v39
	ds_bpermute_b32 v39, v93, v38
	s_waitcnt lgkmcnt(0)
	v_add_f32_e32 v38, v38, v39
	v_fmamk_f32 v38, v38, 0x3a800000, v205
	v_cmp_gt_f32_e32 vcc, s88, v38
	v_mul_f32_e32 v39, 0x4f800000, v38
	s_nop 0
	v_cndmask_b32_e32 v38, v38, v39, vcc
	v_sqrt_f32_e32 v39, v38
	s_nop 0
	v_add_u32_e32 v40, -1, v39
	v_fma_f32 v41, -v40, v39, v38
	v_cmp_ge_f32_e64 s[0:1], 0, v41
	v_add_u32_e32 v41, 1, v39
	s_nop 0
	v_cndmask_b32_e64 v40, v39, v40, s[0:1]
	v_fma_f32 v39, -v41, v39, v38
	v_cmp_lt_f32_e64 s[0:1], 0, v39
	s_nop 1
	v_cndmask_b32_e64 v39, v40, v41, s[0:1]
	v_mul_f32_e32 v40, 0x37800000, v39
	v_cndmask_b32_e32 v39, v39, v40, vcc
	v_cmp_class_f32_e32 vcc, v38, v206
	s_nop 1
	v_cndmask_b32_e32 v38, v39, v38, vcc
	v_div_scale_f32 v39, s[0:1], v38, v38, 1.0
	v_rcp_f32_e32 v40, v39
	s_nop 0
	v_fma_f32 v41, -v39, v40, 1.0
	v_fmac_f32_e32 v40, v41, v40
	v_div_scale_f32 v41, vcc, 1.0, v38, 1.0
	v_mul_f32_e32 v82, v41, v40
	v_fma_f32 v84, -v39, v82, v41
	v_fmac_f32_e32 v82, v84, v40
	v_fma_f32 v39, -v39, v82, v41
	v_div_fmas_f32 v39, v39, v40, v82
	v_div_fixup_f32 v82, v39, v38, 1.0
	s_waitcnt vmcnt(4)
	v_mul_f32_e32 v38, v10, v10
	v_mul_f32_e32 v39, v11, v11
	v_mov_b32_e32 v95, v38
	v_mov_b32_e32 v97, v39
	v_mul_f32_e32 v84, v27, v27
	v_pk_add_f32 v[94:95], v[94:95], v[96:97]
	v_pk_fma_f32 v[96:97], v[26:27], v[26:27], v[84:85] op_sel_hi:[1,1,0]
	v_mul_f32_e32 v84, v29, v29
	v_mul_f32_e32 v40, v12, v12
	v_mul_f32_e32 v41, v13, v13
	v_pk_fma_f32 v[98:99], v[28:29], v[28:29], v[84:85] op_sel_hi:[1,1,0]
	v_mov_b32_e32 v97, v40
	v_mov_b32_e32 v99, v41
	v_pk_add_f32 v[96:97], v[96:97], v[98:99]
	v_pk_mul_f32 v[66:67], v[66:67], v[82:83] op_sel_hi:[1,0]
	v_pk_add_f32 v[94:95], v[94:95], v[96:97]
	s_waitcnt vmcnt(3)
	v_pk_mul_f32 v[96:97], v[58:59], v[58:59]
	v_add_f32_e32 v38, v94, v95
	ds_bpermute_b32 v39, v37, v38
	v_pk_mul_f32 v[94:95], v[60:61], v[60:61]
	v_pk_mul_f32 v[68:69], v[68:69], v[82:83] op_sel_hi:[1,0]
	v_pk_mov_b32 v[98:99], v[96:97], v[94:95] op_sel:[1,0]
	v_mov_b32_e32 v97, v95
	s_waitcnt lgkmcnt(0)
	v_add_f32_e32 v38, v38, v39
	ds_bpermute_b32 v39, v89, v38
	v_pk_add_f32 v[94:95], v[98:99], v[96:97]
	s_waitcnt vmcnt(2)
	v_pk_mul_f32 v[96:97], v[44:45], v[44:45]
	v_pk_mul_f32 v[98:99], v[42:43], v[42:43]
	v_pk_add_f32 v[94:95], v[94:95], v[94:95] op_sel:[0,1] op_sel_hi:[1,0]
	s_waitcnt lgkmcnt(0)
	v_add_f32_e32 v38, v38, v39
	ds_bpermute_b32 v39, v90, v38
	v_pk_mov_b32 v[100:101], v[98:99], v[96:97] op_sel:[1,0]
	v_mov_b32_e32 v99, v97
	v_pk_add_f32 v[96:97], v[100:101], v[98:99]
	v_pk_mul_f32 v[46:47], v[46:47], v[82:83] op_sel_hi:[1,0]
	s_waitcnt lgkmcnt(0)
	v_add_f32_e32 v38, v38, v39
	ds_bpermute_b32 v39, v91, v38
	v_pk_add_f32 v[96:97], v[96:97], v[96:97] op_sel:[0,1] op_sel_hi:[1,0]
	v_pk_mul_f32 v[48:49], v[48:49], v[82:83] op_sel_hi:[1,0]
	v_pk_mul_f32 v[18:19], v[18:19], v[82:83] op_sel_hi:[1,0]
	v_pk_mul_f32 v[20:21], v[20:21], v[82:83] op_sel_hi:[1,0]
	s_waitcnt lgkmcnt(0)
	v_add_f32_e32 v38, v38, v39
	ds_bpermute_b32 v39, v92, v38
	v_pk_mul_f32 v[2:3], v[2:3], v[82:83] op_sel_hi:[1,0]
	v_pk_mul_f32 v[4:5], v[4:5], v[82:83] op_sel_hi:[1,0]
	s_waitcnt lgkmcnt(0)
	v_add_f32_e32 v38, v38, v39
	ds_bpermute_b32 v39, v93, v38
	s_waitcnt lgkmcnt(0)
	v_add_f32_e32 v38, v38, v39
	v_fmamk_f32 v38, v38, 0x3a800000, v205
	v_cmp_gt_f32_e32 vcc, s88, v38
	v_mul_f32_e32 v39, 0x4f800000, v38
	s_nop 0
	v_cndmask_b32_e32 v38, v38, v39, vcc
	v_sqrt_f32_e32 v39, v38
	s_nop 0
	v_add_u32_e32 v40, -1, v39
	v_fma_f32 v41, -v40, v39, v38
	v_cmp_ge_f32_e64 s[0:1], 0, v41
	v_add_u32_e32 v41, 1, v39
	s_nop 0
	v_cndmask_b32_e64 v40, v39, v40, s[0:1]
	v_fma_f32 v39, -v41, v39, v38
	v_cmp_lt_f32_e64 s[0:1], 0, v39
	s_nop 1
	v_cndmask_b32_e64 v39, v40, v41, s[0:1]
	v_mul_f32_e32 v40, 0x37800000, v39
	v_cndmask_b32_e32 v39, v39, v40, vcc
	v_cmp_class_f32_e32 vcc, v38, v206
	s_nop 1
	v_cndmask_b32_e32 v38, v39, v38, vcc
	v_div_scale_f32 v39, s[0:1], v38, v38, 1.0
	v_rcp_f32_e32 v40, v39
	s_nop 0
	v_fma_f32 v41, -v39, v40, 1.0
	v_fmac_f32_e32 v40, v41, v40
	v_div_scale_f32 v41, vcc, 1.0, v38, 1.0
	v_mul_f32_e32 v84, v41, v40
	v_fma_f32 v86, -v39, v84, v41
	v_fmac_f32_e32 v84, v86, v40
	v_fma_f32 v39, -v39, v84, v41
	v_div_fmas_f32 v39, v39, v40, v84
	v_div_fixup_f32 v84, v39, v38, 1.0
	s_waitcnt vmcnt(0)
	v_mul_f32_e32 v38, v6, v6
	v_mul_f32_e32 v39, v7, v7
	v_mov_b32_e32 v95, v38
	v_mov_b32_e32 v97, v39
	v_mul_f32_e32 v86, v23, v23
	v_pk_add_f32 v[94:95], v[94:95], v[96:97]
	v_pk_fma_f32 v[96:97], v[22:23], v[22:23], v[86:87] op_sel_hi:[1,1,0]
	v_mul_f32_e32 v86, v25, v25
	v_mul_f32_e32 v40, v8, v8
	v_mul_f32_e32 v41, v9, v9
	v_pk_fma_f32 v[98:99], v[24:25], v[24:25], v[86:87] op_sel_hi:[1,1,0]
	v_mov_b32_e32 v97, v40
	v_mov_b32_e32 v99, v41
	v_pk_add_f32 v[96:97], v[96:97], v[98:99]
	v_pk_mul_f32 v[62:63], v[62:63], v[84:85] op_sel_hi:[1,0]
	v_pk_add_f32 v[94:95], v[94:95], v[96:97]
	v_pk_mul_f32 v[64:65], v[64:65], v[84:85] op_sel_hi:[1,0]
	v_add_f32_e32 v38, v94, v95
	ds_bpermute_b32 v39, v37, v38
	s_waitcnt lgkmcnt(0)
; __device__ __forceinline__ unsigned pk2(float lo, float hi) { return cvtpk(lo, hi); }
; template <int NR>
; __device__ __forceinline__ void norm_group(int m0, const float* src_lat, const float* src_ctx, bf16* H, const float* gain, const float* mod, int shoff, int scoff, int lane, const float* part, float* ctx_out) {
;     ...
;         rstd[i] = 1.0f / sqrtf(wave_sum(s) * (1.f / D) + EPS); }
;     const float* mr = mod + b * 6144;
; #pragma unroll
;     for (int j = 0; j < 4; ++j) { const int idx = 4 * (lane + 64 * j);
;         const f32x4 g = *(const f32x4*)(gain + idx), sc = *(const f32x4*)(mr + scoff + idx), sh = *(const f32x4*)(mr + shoff + idx);
;         const f32x4 gs = g * (1.f + sc);
; #pragma unroll
;         for (int i = 0; i < NR; ++i) { const f32x4 y = v[i][j] * rstd[i] * gs + sh;
;             v2u o; o.x = pk2(y.x, y.y); o.y = pk2(y.z, y.w);
;             *(v2u*)(H + (size_t)(m0 + i) * D + idx) = o; } }
	v_add_f32_e32 v38, v38, v39
	ds_bpermute_b32 v39, v89, v38
	s_waitcnt lgkmcnt(0)
	v_add_f32_e32 v38, v38, v39
	ds_bpermute_b32 v39, v90, v38
	s_waitcnt lgkmcnt(0)
	v_add_f32_e32 v38, v38, v39
	ds_bpermute_b32 v39, v91, v38
	s_waitcnt lgkmcnt(0)
	v_add_f32_e32 v38, v38, v39
	ds_bpermute_b32 v39, v92, v38
	s_waitcnt lgkmcnt(0)
	v_add_f32_e32 v38, v38, v39
	ds_bpermute_b32 v39, v93, v38
	s_waitcnt lgkmcnt(0)
	v_add_f32_e32 v38, v38, v39
	v_fmamk_f32 v38, v38, 0x3a800000, v205
	v_cmp_gt_f32_e32 vcc, s88, v38
	v_mul_f32_e32 v39, 0x4f800000, v38
	s_nop 0
	v_cndmask_b32_e32 v38, v38, v39, vcc
	v_sqrt_f32_e32 v39, v38
	s_nop 0
	v_add_u32_e32 v40, -1, v39
	v_fma_f32 v41, -v40, v39, v38
	v_cmp_ge_f32_e64 s[0:1], 0, v41
	v_add_u32_e32 v41, 1, v39
	s_nop 0
	v_cndmask_b32_e64 v40, v39, v40, s[0:1]
	v_fma_f32 v39, -v41, v39, v38
	v_cmp_lt_f32_e64 s[0:1], 0, v39
	s_nop 1
	v_cndmask_b32_e64 v39, v40, v41, s[0:1]
	v_mul_f32_e32 v40, 0x37800000, v39
	v_cndmask_b32_e32 v39, v39, v40, vcc
	v_cmp_class_f32_e32 vcc, v38, v206
	s_nop 1
	v_cndmask_b32_e32 v38, v39, v38, vcc
	v_div_scale_f32 v39, s[0:1], v38, v38, 1.0
	s_lshr_b32 s0, s18, 11
	v_rcp_f32_e32 v40, v39
	s_mulk_i32 s0, 0x1800
	s_ashr_i32 s1, s0, 31
	s_lshl_b64 s[0:1], s[0:1], 2
	s_add_u32 s0, s72, s0
	v_fma_f32 v41, -v39, v40, 1.0
	s_addc_u32 s1, s74, s1
	v_fmac_f32_e32 v40, v41, v40
	v_div_scale_f32 v41, vcc, 1.0, v38, 1.0
	s_add_u32 s2, s0, 0x4000
	v_mul_f32_e32 v86, v41, v40
	s_addc_u32 s3, s1, 0
	v_fma_f32 v94, -v39, v86, v41
	s_add_u32 s0, s0, 0x3000
	v_fmac_f32_e32 v86, v94, v40
	s_addc_u32 s1, s1, 0
	global_load_dwordx4 v[94:97], v[78:79], off
	global_load_dwordx4 v[98:101], v34, s[2:3]
	global_load_dwordx4 v[102:105], v34, s[0:1]
	v_fma_f32 v39, -v39, v86, v41
	v_div_fmas_f32 v39, v39, v40, v86
	v_div_fixup_f32 v86, v39, v38, 1.0
	s_add_i32 s10, s8, 1
	s_add_i32 s12, s8, 2
	s_add_i32 s14, s8, 3
	s_ashr_i32 s11, s10, 31
	s_ashr_i32 s13, s12, 31
	v_pk_mul_f32 v[58:59], v[58:59], v[86:87] op_sel_hi:[1,0]
	v_pk_mul_f32 v[60:61], v[60:61], v[86:87] op_sel_hi:[1,0]
	s_ashr_i32 s15, s14, 31
	s_lshl_b64 s[16:17], s[8:9], 11
	s_lshl_b64 s[10:11], s[10:11], 11
	s_lshl_b64 s[12:13], s[12:13], 11
	s_lshl_b64 s[14:15], s[14:15], 11
	v_lshlrev_b32_e32 v38, 1, v83
	v_pk_mul_f32 v[42:43], v[42:43], v[86:87] op_sel_hi:[1,0]
	v_pk_mul_f32 v[44:45], v[44:45], v[86:87] op_sel_hi:[1,0]
	s_waitcnt vmcnt(1)
	v_pk_add_f32 v[100:101], v[100:101], 1.0 op_sel_hi:[1,0]
	v_pk_add_f32 v[98:99], v[98:99], 1.0 op_sel_hi:[1,0]
	v_pk_mul_f32 v[96:97], v[96:97], v[100:101]
	v_pk_mul_f32 v[94:95], v[94:95], v[98:99]
	s_waitcnt vmcnt(0)
	v_pk_fma_f32 v[72:73], v[72:73], v[96:97], v[104:105]
	v_pk_fma_f32 v[70:71], v[70:71], v[94:95], v[102:103]
	v_pk_fma_f32 v[68:69], v[68:69], v[96:97], v[104:105]
	v_pk_fma_f32 v[66:67], v[66:67], v[94:95], v[102:103]
	v_pk_fma_f32 v[64:65], v[64:65], v[96:97], v[104:105]
	v_pk_fma_f32 v[62:63], v[62:63], v[94:95], v[102:103]
	v_pk_fma_f32 v[60:61], v[96:97], v[60:61], v[104:105]
	v_pk_fma_f32 v[58:59], v[94:95], v[58:59], v[102:103]
	v_cvt_pk_bf16_f32 v70, v70, v71
	v_cvt_pk_bf16_f32 v71, v72, v73
	v_lshl_add_u64 v[72:73], v[74:75], 0, s[16:17]
	v_cvt_pk_bf16_f32 v66, v66, v67
	v_cvt_pk_bf16_f32 v67, v68, v69
	v_lshl_add_u64 v[68:69], v[74:75], 0, s[10:11]
	v_cvt_pk_bf16_f32 v62, v62, v63
	v_cvt_pk_bf16_f32 v63, v64, v65
	v_lshl_add_u64 v[64:65], v[74:75], 0, s[12:13]
	v_cvt_pk_bf16_f32 v58, v58, v59
	v_cvt_pk_bf16_f32 v59, v60, v61
	v_lshl_add_u64 v[60:61], v[74:75], 0, s[14:15]
	global_store_dwordx2 v[72:73], v[70:71], off sc1 nt
	global_store_dwordx2 v[68:69], v[66:67], off sc1 nt
	global_store_dwordx2 v[64:65], v[62:63], off sc1 nt
	global_store_dwordx2 v[60:61], v[58:59], off sc1 nt
	v_lshlrev_b32_e32 v62, 2, v83
	global_load_dwordx4 v[58:61], v[78:79], off offset:1024
	global_load_dwordx4 v[64:67], v62, s[2:3]
	global_load_dwordx4 v[68:71], v62, s[0:1]
	s_add_u32 s16, s90, s16
	s_addc_u32 s17, s91, s17
	s_add_u32 s10, s90, s10
	s_addc_u32 s11, s91, s11
	s_add_u32 s12, s90, s12
	s_addc_u32 s13, s91, s13
	s_add_u32 s14, s90, s14
	s_addc_u32 s15, s91, s15
	s_add_i32 s18, s18, s52
	s_add_i32 s8, s8, s59
	s_cmpk_gt_i32 s18, 0x1fff
	s_waitcnt vmcnt(1)
	v_pk_add_f32 v[64:65], v[64:65], 1.0 op_sel_hi:[1,0]
	v_pk_add_f32 v[62:63], v[66:67], 1.0 op_sel_hi:[1,0]
	v_pk_mul_f32 v[58:59], v[58:59], v[64:65]
	v_pk_mul_f32 v[60:61], v[60:61], v[62:63]
	s_waitcnt vmcnt(0)
; __device__ __forceinline__ unsigned pk2(float lo, float hi) { return cvtpk(lo, hi); }
; template <int NR>
; __device__ __forceinline__ void norm_group(int m0, const float* src_lat, const float* src_ctx, bf16* H, const float* gain, const float* mod, int shoff, int scoff, int lane, const float* part, float* ctx_out) {
;     ...
;     const float* mr = mod + b * 6144;
; #pragma unroll
;     for (int j = 0; j < 4; ++j) { const int idx = 4 * (lane + 64 * j);
;         const f32x4 g = *(const f32x4*)(gain + idx), sc = *(const f32x4*)(mr + scoff + idx), sh = *(const f32x4*)(mr + shoff + idx);
;         const f32x4 gs = g * (1.f + sc);
; #pragma unroll
;         for (int i = 0; i < NR; ++i) { const f32x4 y = v[i][j] * rstd[i] * gs + sh;
;             v2u o; o.x = pk2(y.x, y.y); o.y = pk2(y.z, y.w);
;             *(v2u*)(H + (size_t)(m0 + i) * D + idx) = o; } }
	v_pk_fma_f32 v[46:47], v[46:47], v[58:59], v[68:69]
	v_pk_fma_f32 v[48:49], v[48:49], v[60:61], v[70:71]
	v_cvt_pk_bf16_f32 v46, v46, v47
	v_pk_fma_f32 v[54:55], v[54:55], v[58:59], v[68:69]
	v_cvt_pk_bf16_f32 v47, v48, v49
	global_store_dwordx2 v38, v[46:47], s[10:11] sc1 nt
	v_pk_mul_f32 v[46:47], v[50:51], v[84:85] op_sel_hi:[1,0]
	v_pk_mul_f32 v[48:49], v[52:53], v[84:85] op_sel_hi:[1,0]
	v_pk_fma_f32 v[46:47], v[46:47], v[58:59], v[68:69]
	v_pk_fma_f32 v[42:43], v[42:43], v[58:59], v[68:69]
	v_pk_fma_f32 v[56:57], v[56:57], v[60:61], v[70:71]
	v_cvt_pk_bf16_f32 v54, v54, v55
	v_pk_fma_f32 v[48:49], v[48:49], v[60:61], v[70:71]
	v_cvt_pk_bf16_f32 v55, v56, v57
	global_store_dwordx2 v38, v[54:55], s[16:17] sc1 nt
	v_cvt_pk_bf16_f32 v46, v46, v47
	v_cvt_pk_bf16_f32 v47, v48, v49
	global_store_dwordx2 v38, v[46:47], s[12:13] sc1 nt
	v_pk_fma_f32 v[44:45], v[44:45], v[60:61], v[70:71]
	v_cvt_pk_bf16_f32 v42, v42, v43
	s_nop 0
	v_cvt_pk_bf16_f32 v43, v44, v45
	global_store_dwordx2 v38, v[42:43], s[14:15] sc1 nt
	v_lshlrev_b32_e32 v38, 2, v85
	global_load_dwordx4 v[42:45], v[78:79], off offset:2048
	global_load_dwordx4 v[46:49], v38, s[2:3]
	global_load_dwordx4 v[50:53], v38, s[0:1]
	s_waitcnt vmcnt(1)
	v_pk_add_f32 v[48:49], v[48:49], 1.0 op_sel_hi:[1,0]
	v_pk_add_f32 v[46:47], v[46:47], 1.0 op_sel_hi:[1,0]
	v_pk_mul_f32 v[44:45], v[44:45], v[48:49]
	v_pk_mul_f32 v[42:43], v[42:43], v[46:47]
	s_waitcnt vmcnt(0)
	v_pk_fma_f32 v[32:33], v[32:33], v[44:45], v[52:53]
	v_pk_fma_f32 v[30:31], v[30:31], v[42:43], v[50:51]
	v_pk_fma_f32 v[18:19], v[18:19], v[42:43], v[50:51]
	v_cvt_pk_bf16_f32 v30, v30, v31
	v_cvt_pk_bf16_f32 v31, v32, v33
	v_lshlrev_b32_e32 v32, 1, v85
	v_pk_fma_f32 v[20:21], v[20:21], v[44:45], v[52:53]
	v_cvt_pk_bf16_f32 v18, v18, v19
	global_store_dwordx2 v32, v[30:31], s[16:17] sc1 nt
	v_cvt_pk_bf16_f32 v19, v20, v21
	global_store_dwordx2 v32, v[18:19], s[10:11] sc1 nt
	v_pk_mul_f32 v[18:19], v[26:27], v[84:85] op_sel_hi:[1,0]
	v_pk_mul_f32 v[20:21], v[28:29], v[84:85] op_sel_hi:[1,0]
	v_pk_fma_f32 v[18:19], v[18:19], v[42:43], v[50:51]
	v_pk_fma_f32 v[20:21], v[20:21], v[44:45], v[52:53]
	v_cvt_pk_bf16_f32 v18, v18, v19
	v_lshlrev_b32_e32 v26, 2, v87
	v_cvt_pk_bf16_f32 v19, v20, v21
	global_store_dwordx2 v32, v[18:19], s[12:13] sc1 nt
	v_pk_mul_f32 v[18:19], v[22:23], v[86:87] op_sel_hi:[1,0]
	v_pk_mul_f32 v[20:21], v[24:25], v[86:87] op_sel_hi:[1,0]
	v_pk_fma_f32 v[18:19], v[18:19], v[42:43], v[50:51]
	v_pk_fma_f32 v[20:21], v[20:21], v[44:45], v[52:53]
	v_cvt_pk_bf16_f32 v18, v18, v19
	s_nop 0
	v_cvt_pk_bf16_f32 v19, v20, v21
	global_store_dwordx2 v32, v[18:19], s[14:15] sc1 nt
	global_load_dwordx4 v[18:21], v[78:79], off offset:3072
	s_nop 0
	global_load_dwordx4 v[22:25], v26, s[2:3]
	s_nop 0
	global_load_dwordx4 v[26:29], v26, s[0:1]
	s_waitcnt vmcnt(1)
	v_pk_add_f32 v[24:25], v[24:25], 1.0 op_sel_hi:[1,0]
	v_pk_add_f32 v[22:23], v[22:23], 1.0 op_sel_hi:[1,0]
	v_pk_mul_f32 v[20:21], v[20:21], v[24:25]
	v_pk_mul_f32 v[18:19], v[18:19], v[22:23]
	s_waitcnt vmcnt(0)
	v_pk_fma_f32 v[16:17], v[16:17], v[20:21], v[28:29]
	v_pk_fma_f32 v[14:15], v[14:15], v[18:19], v[26:27]
	v_pk_fma_f32 v[2:3], v[2:3], v[18:19], v[26:27]
	v_cvt_pk_bf16_f32 v14, v14, v15
	v_cvt_pk_bf16_f32 v15, v16, v17
	v_lshlrev_b32_e32 v16, 1, v87
	v_pk_fma_f32 v[4:5], v[4:5], v[20:21], v[28:29]
	v_cvt_pk_bf16_f32 v2, v2, v3
	global_store_dwordx2 v16, v[14:15], s[16:17] sc1 nt
	v_cvt_pk_bf16_f32 v3, v4, v5
	global_store_dwordx2 v16, v[2:3], s[10:11] sc1 nt
	v_pk_mul_f32 v[2:3], v[10:11], v[84:85] op_sel_hi:[1,0]
	v_pk_mul_f32 v[4:5], v[12:13], v[84:85] op_sel_hi:[1,0]
	v_pk_fma_f32 v[2:3], v[2:3], v[18:19], v[26:27]
	v_pk_fma_f32 v[4:5], v[4:5], v[20:21], v[28:29]
	v_cvt_pk_bf16_f32 v2, v2, v3
	s_nop 0
	v_cvt_pk_bf16_f32 v3, v4, v5
	global_store_dwordx2 v16, v[2:3], s[12:13] sc1 nt
	v_pk_mul_f32 v[2:3], v[6:7], v[86:87] op_sel_hi:[1,0]
	v_pk_mul_f32 v[4:5], v[8:9], v[86:87] op_sel_hi:[1,0]
	v_pk_fma_f32 v[2:3], v[2:3], v[18:19], v[26:27]
	v_pk_fma_f32 v[4:5], v[4:5], v[20:21], v[28:29]
	v_cvt_pk_bf16_f32 v2, v2, v3
	s_nop 0
	v_cvt_pk_bf16_f32 v3, v4, v5
	global_store_dwordx2 v16, v[2:3], s[14:15] sc1 nt
	s_cbranch_scc0 .LBB0_615

; __device__ __forceinline__ unsigned pk2(float lo, float hi) { return cvtpk(lo, hi); }
; template <int NR>
; __device__ __forceinline__ void norm_group(int m0, const float* src_lat, const float* src_ctx, bf16* H, const float* gain, const float* mod, int shoff, int scoff, int lane, const float* part, float* ctx_out) {
;     const float* xr = (m0 < MLAT) ? src_lat + (size_t)m0 * D : src_ctx + (size_t)(m0 - MLAT) * D;
;     const int b = (m0 < MLAT) ? (m0 >> 13) : 4;
;     f32x4 v[NR][4]; float rstd[NR];
; #pragma unroll
;     for (int i = 0; i < NR; ++i)
; #pragma unroll
;         for (int j = 0; j < 4; ++j) v[i][j] = *((const f32x4*)(xr + (size_t)i * D) + lane + 64 * j);
;     if (part && m0 >= MLAT) {
; #pragma unroll
;         for (int i = 0; i < NR; ++i)
; #pragma unroll
;             for (int j = 0; j < 4; ++j) { const size_t o = (size_t)(m0 - MLAT + i) * D + 4 * (lane + 64 * j);
;                 const f32x4 p0 = *(const f32x4*)(part + o), p1 = *(const f32x4*)(part + (size_t)MCTX * D + o), p2 = *(const f32x4*)(part + (size_t)2 * MCTX * D + o), p3 = *(const f32x4*)(part + (size_t)3 * MCTX * D + o);
;                 v[i][j] = v[i][j] + ((p0 + p1) + (p2 + p3)); *(f32x4*)(ctx_out + o) = v[i][j]; }
;     }
; #pragma unroll
;     for (int i = 0; i < NR; ++i) { float s = 0.f;
; #pragma unroll
;         for (int j = 0; j < 4; ++j) s += (v[i][j].x * v[i][j].x + v[i][j].y * v[i][j].y) + (v[i][j].z * v[i][j].z + v[i][j].w * v[i][j].w);
;         rstd[i] = 1.0f / sqrtf(wave_sum(s) * (1.f / D) + EPS); }
;     const float* mr = mod + b * 6144;
; #pragma unroll
;     for (int j = 0; j < 4; ++j) { const int idx = 4 * (lane + 64 * j);
;         const f32x4 g = *(const f32x4*)(gain + idx), sc = *(const f32x4*)(mr + scoff + idx), sh = *(const f32x4*)(mr + shoff + idx);
;         const f32x4 gs = g * (1.f + sc);
; #pragma unroll
;         for (int i = 0; i < NR; ++i) { const f32x4 y = v[i][j] * rstd[i] * gs + sh;
;             v2u o; o.x = pk2(y.x, y.y); o.y = pk2(y.z, y.w);
;             *(v2u*)(H + (size_t)(m0 + i) * D + idx) = o; } }
.LBB0_618:
	s_waitcnt vmcnt(3)
	v_pk_mul_f32 v[42:43], v[16:17], v[16:17]
	v_pk_mul_f32 v[44:45], v[14:15], v[14:15]
	s_waitcnt vmcnt(2)
	v_pk_mul_f32 v[30:31], v[12:13], v[12:13]
	v_pk_mul_f32 v[32:33], v[10:11], v[10:11]
	v_pk_mov_b32 v[46:47], v[44:45], v[42:43] op_sel:[1,0]
	v_mov_b32_e32 v45, v43
	v_pk_add_f32 v[42:43], v[46:47], v[44:45]
	v_pk_mov_b32 v[44:45], v[32:33], v[30:31] op_sel:[1,0]
	v_mov_b32_e32 v33, v31
	s_waitcnt vmcnt(1)
	v_mul_f32_e32 v22, v6, v6
	v_pk_add_f32 v[30:31], v[44:45], v[32:33]
	v_pk_fma_f32 v[32:33], v[6:7], v[6:7], v[22:23] op_sel_hi:[1,1,0]
	v_mul_f32_e32 v22, v8, v8
	v_pk_add_f32 v[42:43], v[42:43], v[42:43] op_sel_hi:[0,1]
	v_pk_add_f32 v[30:31], v[30:31], v[30:31] op_sel_hi:[0,1]
	v_pk_fma_f32 v[44:45], v[8:9], v[8:9], v[22:23] op_sel_hi:[1,1,0]
	s_waitcnt vmcnt(0)
	v_mul_f32_e32 v32, v2, v2
	v_mul_f32_e32 v44, v3, v3
	v_mul_f32_e32 v42, v4, v4
	v_mul_f32_e32 v30, v5, v5
	v_pk_add_f32 v[32:33], v[32:33], v[44:45]
	v_pk_add_f32 v[30:31], v[42:43], v[30:31]
	s_min_i32 s0, s6, 0x8000
	v_pk_add_f32 v[30:31], v[32:33], v[30:31]
	s_ashr_i32 s6, s0, 13
	v_add_f32_e32 v22, v30, v31
	ds_bpermute_b32 v29, v23, v22
	s_waitcnt lgkmcnt(0)
	v_add_f32_e32 v22, v22, v29
	ds_bpermute_b32 v29, v24, v22
	s_waitcnt lgkmcnt(0)
	v_add_f32_e32 v22, v22, v29
	ds_bpermute_b32 v29, v25, v22
	s_waitcnt lgkmcnt(0)
	v_add_f32_e32 v22, v22, v29
	ds_bpermute_b32 v29, v26, v22
	s_waitcnt lgkmcnt(0)
	v_add_f32_e32 v22, v22, v29
	ds_bpermute_b32 v29, v27, v22
	s_waitcnt lgkmcnt(0)
	v_add_f32_e32 v22, v22, v29
	ds_bpermute_b32 v29, v28, v22
	s_waitcnt lgkmcnt(0)
	v_add_f32_e32 v22, v22, v29
	v_fmamk_f32 v22, v22, 0x3a800000, v205
	v_cmp_gt_f32_e32 vcc, s88, v22
	v_mul_f32_e32 v29, 0x4f800000, v22
	s_nop 0
	v_cndmask_b32_e32 v22, v22, v29, vcc
	v_sqrt_f32_e32 v29, v22
	s_nop 0
	v_add_u32_e32 v30, -1, v29
	v_fma_f32 v31, -v30, v29, v22
	v_cmp_ge_f32_e64 s[0:1], 0, v31
	v_add_u32_e32 v31, 1, v29
	s_nop 0
	v_cndmask_b32_e64 v30, v29, v30, s[0:1]
	v_fma_f32 v29, -v31, v29, v22
	v_cmp_lt_f32_e64 s[0:1], 0, v29
	s_nop 1
	v_cndmask_b32_e64 v29, v30, v31, s[0:1]
	v_mul_f32_e32 v30, 0x37800000, v29
	v_cndmask_b32_e32 v29, v29, v30, vcc
	v_cmp_class_f32_e32 vcc, v22, v206
	s_nop 1
	v_cndmask_b32_e32 v22, v29, v22, vcc
	v_div_scale_f32 v29, s[0:1], v22, v22, 1.0
	v_rcp_f32_e32 v30, v29
	s_mul_i32 s0, s6, 0x1800
	s_ashr_i32 s1, s0, 31
	s_lshl_b64 s[0:1], s[0:1], 2
	v_fma_f32 v31, -v29, v30, 1.0
	v_fmac_f32_e32 v30, v31, v30
	v_div_scale_f32 v31, vcc, 1.0, v22, 1.0
	s_add_u32 s0, s72, s0
	v_mul_f32_e32 v32, v31, v30
	s_addc_u32 s1, s74, s1
	v_fma_f32 v33, -v29, v32, v31
	s_add_u32 s6, s0, 0x4000
	v_fmac_f32_e32 v32, v33, v30
	s_addc_u32 s7, s1, 0
	v_fma_f32 v29, -v29, v32, v31
	s_add_u32 s0, s0, 0x3000
	v_div_fmas_f32 v29, v29, v30, v32
	s_addc_u32 s1, s1, 0
	global_load_dwordx4 v[30:33], v[18:19], off
	global_load_dwordx4 v[42:45], v34, s[6:7]
	global_load_dwordx4 v[46:49], v34, s[0:1]
	v_div_fixup_f32 v22, v29, v22, 1.0
	v_pk_mul_f32 v[14:15], v[14:15], v[22:23] op_sel_hi:[1,0]
	v_pk_mul_f32 v[16:17], v[16:17], v[22:23] op_sel_hi:[1,0]
	v_lshlrev_b32_e32 v29, 2, v83
	v_pk_mul_f32 v[10:11], v[10:11], v[22:23] op_sel_hi:[1,0]
	v_pk_mul_f32 v[12:13], v[12:13], v[22:23] op_sel_hi:[1,0]
	v_pk_mul_f32 v[6:7], v[6:7], v[22:23] op_sel_hi:[1,0]
	v_pk_mul_f32 v[8:9], v[8:9], v[22:23] op_sel_hi:[1,0]
	s_add_i32 s78, s78, s52
	v_pk_mul_f32 v[2:3], v[2:3], v[22:23] op_sel_hi:[1,0]
	v_pk_mul_f32 v[4:5], v[4:5], v[22:23] op_sel_hi:[1,0]
	s_waitcnt vmcnt(1)
	v_pk_add_f32 v[42:43], v[42:43], 1.0 op_sel_hi:[1,0]
	v_pk_add_f32 v[44:45], v[44:45], 1.0 op_sel_hi:[1,0]
	v_pk_mul_f32 v[30:31], v[30:31], v[42:43]
	v_pk_mul_f32 v[32:33], v[32:33], v[44:45]
	s_waitcnt vmcnt(0)
	v_pk_fma_f32 v[14:15], v[30:31], v[14:15], v[46:47]
	v_pk_fma_f32 v[16:17], v[32:33], v[16:17], v[48:49]
	v_cvt_pk_bf16_f32 v14, v14, v15
	s_nop 0
	v_cvt_pk_bf16_f32 v15, v16, v17
	global_store_dwordx2 v[20:21], v[14:15], off sc1 nt
	global_load_dwordx4 v[14:17], v[18:19], off offset:1024
	s_nop 0
	global_load_dwordx4 v[30:33], v29, s[6:7]
	global_load_dwordx4 v[42:45], v29, s[0:1]
	v_lshlrev_b32_e32 v29, 2, v85
	s_waitcnt vmcnt(1)
	v_pk_add_f32 v[30:31], v[30:31], 1.0 op_sel_hi:[1,0]
	v_pk_add_f32 v[32:33], v[32:33], 1.0 op_sel_hi:[1,0]
	v_pk_mul_f32 v[14:15], v[14:15], v[30:31]
	v_pk_mul_f32 v[16:17], v[16:17], v[32:33]
	s_waitcnt vmcnt(0)
	v_pk_fma_f32 v[10:11], v[14:15], v[10:11], v[42:43]
	v_pk_fma_f32 v[12:13], v[16:17], v[12:13], v[44:45]
	v_cvt_pk_bf16_f32 v10, v10, v11
	s_nop 0
	v_cvt_pk_bf16_f32 v11, v12, v13
	global_store_dwordx2 v[20:21], v[10:11], off offset:512 sc1 nt
	global_load_dwordx4 v[10:13], v[18:19], off offset:2048
	s_nop 0
	global_load_dwordx4 v[14:17], v29, s[6:7]
	global_load_dwordx4 v[30:33], v29, s[0:1]
	s_waitcnt vmcnt(1)
	v_pk_add_f32 v[14:15], v[14:15], 1.0 op_sel_hi:[1,0]
	v_pk_add_f32 v[16:17], v[16:17], 1.0 op_sel_hi:[1,0]
	v_pk_mul_f32 v[10:11], v[10:11], v[14:15]
	v_pk_mul_f32 v[12:13], v[12:13], v[16:17]
	s_waitcnt vmcnt(0)
	v_pk_fma_f32 v[6:7], v[6:7], v[10:11], v[30:31]
	v_pk_fma_f32 v[8:9], v[8:9], v[12:13], v[32:33]
	v_cvt_pk_bf16_f32 v6, v6, v7
	v_lshlrev_b32_e32 v14, 2, v87
	v_cvt_pk_bf16_f32 v7, v8, v9
	global_store_dwordx2 v[20:21], v[6:7], off offset:1024 sc1 nt
	global_load_dwordx4 v[6:9], v[18:19], off offset:3072
	s_nop 0
	global_load_dwordx4 v[10:13], v14, s[6:7]
	s_nop 0
	global_load_dwordx4 v[14:17], v14, s[0:1]
	s_add_i32 s0, s78, 0x8000
	s_add_u32 s2, s2, s52
	s_addc_u32 s3, s3, s53
	s_cmp_lt_i32 s0, s14
	s_waitcnt vmcnt(1)
	v_pk_add_f32 v[10:11], v[10:11], 1.0 op_sel_hi:[1,0]
	v_pk_add_f32 v[12:13], v[12:13], 1.0 op_sel_hi:[1,0]
	v_pk_mul_f32 v[6:7], v[6:7], v[10:11]
	v_pk_mul_f32 v[8:9], v[8:9], v[12:13]
	s_waitcnt vmcnt(0)
	v_pk_fma_f32 v[2:3], v[2:3], v[6:7], v[14:15]
	v_pk_fma_f32 v[4:5], v[4:5], v[8:9], v[16:17]
	v_cvt_pk_bf16_f32 v2, v2, v3
	s_nop 0
	v_cvt_pk_bf16_f32 v3, v4, v5
	global_store_dwordx2 v[20:21], v[2:3], off offset:1536 sc1 nt
	v_lshl_add_u64 v[20:21], v[20:21], 0, s[66:67]
	s_cbranch_scc0 .LBB0_623

; template <int NR>
; __device__ __forceinline__ void norm_group(int m0, const float* src_lat, const float* src_ctx, bf16* H, const float* gain, const float* mod, int shoff, int scoff, int lane, const float* part, float* ctx_out) {
;     ...
;     if (part && m0 >= MLAT) {
; #pragma unroll
;         for (int i = 0; i < NR; ++i)
; #pragma unroll
;             for (int j = 0; j < 4; ++j) { const size_t o = (size_t)(m0 - MLAT + i) * D + 4 * (lane + 64 * j);
;                 const f32x4 p0 = *(const f32x4*)(part + o), p1 = *(const f32x4*)(part + (size_t)MCTX * D + o), p2 = *(const f32x4*)(part + (size_t)2 * MCTX * D + o), p3 = *(const f32x4*)(part + (size_t)3 * MCTX * D + o);
;                 v[i][j] = v[i][j] + ((p0 + p1) + (p2 + p3)); *(f32x4*)(ctx_out + o) = v[i][j]; }
.LBB0_621:
	s_andn2_b64 vcc, exec, s[0:1]
	s_cbranch_vccnz .LBB0_618
	s_lshl_b64 s[0:1], s[78:79], 10
	v_mov_b32_e32 v31, s1
	v_or_b32_e32 v30, s0, v81
	v_lshlrev_b64 v[54:55], 2, v[30:31]
	v_lshl_add_u64 v[30:31], s[50:51], 0, v[54:55]
	v_lshl_add_u64 v[42:43], s[8:9], 0, v[54:55]
	v_lshl_add_u64 v[46:47], s[10:11], 0, v[54:55]
	v_lshl_add_u64 v[50:51], s[12:13], 0, v[54:55]
	global_load_dwordx4 v[30:33], v[30:31], off
	s_nop 0
	global_load_dwordx4 v[42:45], v[42:43], off
	s_nop 0
	global_load_dwordx4 v[46:49], v[46:47], off
	s_waitcnt vmcnt(1)
	v_pk_add_f32 v[32:33], v[32:33], v[44:45]
	global_load_dwordx4 v[50:53], v[50:51], off
	v_pk_add_f32 v[30:31], v[30:31], v[42:43]
	s_waitcnt vmcnt(0)
	v_pk_add_f32 v[42:43], v[48:49], v[52:53]
	v_pk_add_f32 v[44:45], v[46:47], v[50:51]
	v_pk_add_f32 v[32:33], v[32:33], v[42:43]
	v_pk_add_f32 v[30:31], v[30:31], v[44:45]
	v_pk_add_f32 v[16:17], v[16:17], v[32:33]
	v_pk_add_f32 v[14:15], v[14:15], v[30:31]
	v_lshl_add_u64 v[30:31], s[94:95], 0, v[54:55]
	global_store_dwordx4 v[30:31], v[14:17], off sc1 nt
	v_mov_b32_e32 v31, s1
	v_or_b32_e32 v30, s0, v83
	v_lshlrev_b64 v[54:55], 2, v[30:31]
	v_lshl_add_u64 v[30:31], s[50:51], 0, v[54:55]
	v_lshl_add_u64 v[42:43], s[8:9], 0, v[54:55]
	v_lshl_add_u64 v[46:47], s[10:11], 0, v[54:55]
	v_lshl_add_u64 v[50:51], s[12:13], 0, v[54:55]
	global_load_dwordx4 v[30:33], v[30:31], off
	s_nop 0
	global_load_dwordx4 v[42:45], v[42:43], off
	s_nop 0
	global_load_dwordx4 v[46:49], v[46:47], off
	s_waitcnt vmcnt(1)
	v_pk_add_f32 v[32:33], v[32:33], v[44:45]
	global_load_dwordx4 v[50:53], v[50:51], off
	v_pk_add_f32 v[30:31], v[30:31], v[42:43]
	s_waitcnt vmcnt(0)
	v_pk_add_f32 v[42:43], v[48:49], v[52:53]
	v_pk_add_f32 v[44:45], v[46:47], v[50:51]
	v_pk_add_f32 v[32:33], v[32:33], v[42:43]
	v_pk_add_f32 v[30:31], v[30:31], v[44:45]
	v_pk_add_f32 v[12:13], v[12:13], v[32:33]
	v_pk_add_f32 v[10:11], v[10:11], v[30:31]
	v_lshl_add_u64 v[30:31], s[94:95], 0, v[54:55]
	global_store_dwordx4 v[30:31], v[10:13], off sc1 nt
	v_mov_b32_e32 v31, s1
	v_or_b32_e32 v30, s0, v85
	v_lshlrev_b64 v[54:55], 2, v[30:31]
	v_lshl_add_u64 v[30:31], s[50:51], 0, v[54:55]
	v_lshl_add_u64 v[42:43], s[8:9], 0, v[54:55]
	v_lshl_add_u64 v[46:47], s[10:11], 0, v[54:55]
	v_lshl_add_u64 v[50:51], s[12:13], 0, v[54:55]
	global_load_dwordx4 v[30:33], v[30:31], off
	s_nop 0
	global_load_dwordx4 v[42:45], v[42:43], off
	s_nop 0
	global_load_dwordx4 v[46:49], v[46:47], off
	s_waitcnt vmcnt(1)
	v_pk_add_f32 v[32:33], v[32:33], v[44:45]
	global_load_dwordx4 v[50:53], v[50:51], off
	v_pk_add_f32 v[30:31], v[30:31], v[42:43]
	s_waitcnt vmcnt(0)
	v_pk_add_f32 v[42:43], v[48:49], v[52:53]
	v_pk_add_f32 v[44:45], v[46:47], v[50:51]
	v_pk_add_f32 v[32:33], v[32:33], v[42:43]
	v_pk_add_f32 v[30:31], v[30:31], v[44:45]
	v_pk_add_f32 v[8:9], v[8:9], v[32:33]
	v_pk_add_f32 v[6:7], v[6:7], v[30:31]
	v_lshl_add_u64 v[30:31], s[94:95], 0, v[54:55]
	global_store_dwordx4 v[30:31], v[6:9], off sc1 nt
	v_mov_b32_e32 v31, s1
	v_or_b32_e32 v30, s0, v87
	v_lshlrev_b64 v[54:55], 2, v[30:31]
	v_lshl_add_u64 v[30:31], s[50:51], 0, v[54:55]
	v_lshl_add_u64 v[42:43], s[8:9], 0, v[54:55]
	v_lshl_add_u64 v[46:47], s[10:11], 0, v[54:55]
	v_lshl_add_u64 v[50:51], s[12:13], 0, v[54:55]
	global_load_dwordx4 v[30:33], v[30:31], off
	s_nop 0
	global_load_dwordx4 v[42:45], v[42:43], off
	s_nop 0
	global_load_dwordx4 v[46:49], v[46:47], off
	s_waitcnt vmcnt(1)
	v_pk_add_f32 v[32:33], v[32:33], v[44:45]
	global_load_dwordx4 v[50:53], v[50:51], off
	v_pk_add_f32 v[30:31], v[30:31], v[42:43]
	s_waitcnt vmcnt(0)
	v_pk_add_f32 v[42:43], v[48:49], v[52:53]
	v_pk_add_f32 v[44:45], v[46:47], v[50:51]
	v_pk_add_f32 v[32:33], v[32:33], v[42:43]
	v_pk_add_f32 v[30:31], v[30:31], v[44:45]
	v_pk_add_f32 v[4:5], v[4:5], v[32:33]
	v_pk_add_f32 v[2:3], v[2:3], v[30:31]
	v_lshl_add_u64 v[30:31], s[94:95], 0, v[54:55]
	global_store_dwordx4 v[30:31], v[2:5], off sc1 nt
	s_branch .LBB0_618
